# batched loads in LRU pass1, adaLN init loop, NA epilogue, phase A; NA V operand via ds_read_b64_tr_b16; phase D item rebalancing
# speedup vs baseline: 1.0255x; 1.0255x over previous
; __global__ void __launch_bounds__(512, 2) mk_fwd(Args args) {
;     ...
;         for (int it = bid; it < DEPTH * 96; it += G) {
;             const int L = it / 96, cb = it % 96, ksl = tid >> 6, col = cb * 64 + (tid & 63);
;             float a5[5] = {0.f, 0.f, 0.f, 0.f, 0.f};
;             const float* wp = ada_w + (size_t)L * DM * 6144 + col;
;             for (int k = ksl * 256; k < ksl * 256 + 256; ++k) { const float w = wp[(size_t)k * 6144];
; #pragma unroll
;                 for (int r = 0; r < 5; ++r) a5[r] += sil[r * 2048 + k] * w; }
.LBB0_90:
	s_mul_hi_i32 s0, s17, 0x2aaaaaab
	s_lshr_b32 s1, s0, 31
	s_ashr_i32 s0, s0, 4
	s_add_i32 s18, s0, s1
	s_mul_i32 s0, s18, 0x60
	s_sub_i32 s0, s17, s0
	s_lshl_b32 s12, s0, 6
	v_or_b32_e32 v12, s12, v8
	v_ashrrev_i32_e32 v13, 31, v12
	v_lshlrev_b64 v[12:13], 2, v[12:13]
	v_mad_i64_i32 v[12:13], s[0:1], s18, v18, v[12:13]
	v_lshl_add_u64 v[12:13], v[4:5], 0, v[12:13]
	s_mov_b32 s13, 0
	v_mov_b32_e32 v14, 0
	v_mov_b32_e32 v15, v3
	v_mov_b32_e32 v16, 0
	v_mov_b32_e32 v17, v3
	v_mov_b32_e32 v20, 0
	s_mov_b32 s24, 0x6000
	s_mov_b32 s25, 0
	s_mov_b32 s26, 0xfffee000
	s_mov_b32 s27, -1
	v_lshl_add_u64 v[22:23], v[12:13], 0, s[26:27]
.Lada_kloop:
	global_load_dword v120, v[22:23], off
	v_lshl_add_u64 v[22:23], v[22:23], 0, s[24:25]
	global_load_dword v121, v[22:23], off
	v_lshl_add_u64 v[22:23], v[22:23], 0, s[24:25]
	global_load_dword v122, v[22:23], off
	v_lshl_add_u64 v[22:23], v[22:23], 0, s[24:25]
	global_load_dword v123, v[22:23], off
	v_lshl_add_u64 v[22:23], v[22:23], 0, s[24:25]
	global_load_dword v124, v[22:23], off
	v_lshl_add_u64 v[22:23], v[22:23], 0, s[24:25]
	global_load_dword v125, v[22:23], off
	v_lshl_add_u64 v[22:23], v[22:23], 0, s[24:25]
	global_load_dword v126, v[22:23], off
	v_lshl_add_u64 v[22:23], v[22:23], 0, s[24:25]
	global_load_dword v127, v[22:23], off
	v_lshl_add_u64 v[22:23], v[22:23], 0, s[24:25]
	global_load_dword v128, v[22:23], off
	v_lshl_add_u64 v[22:23], v[22:23], 0, s[24:25]
	global_load_dword v129, v[22:23], off
	v_lshl_add_u64 v[22:23], v[22:23], 0, s[24:25]
	global_load_dword v130, v[22:23], off
	v_lshl_add_u64 v[22:23], v[22:23], 0, s[24:25]
	global_load_dword v131, v[22:23], off
	v_lshl_add_u64 v[22:23], v[22:23], 0, s[24:25]
	global_load_dword v132, v[22:23], off
	v_lshl_add_u64 v[22:23], v[22:23], 0, s[24:25]
	global_load_dword v133, v[22:23], off
	v_lshl_add_u64 v[22:23], v[22:23], 0, s[24:25]
	global_load_dword v134, v[22:23], off
	v_lshl_add_u64 v[22:23], v[22:23], 0, s[24:25]
	global_load_dword v135, v[22:23], off
	v_lshl_add_u64 v[22:23], v[22:23], 0, s[24:25]
	global_load_dword v136, v[22:23], off
	v_lshl_add_u64 v[22:23], v[22:23], 0, s[24:25]
	global_load_dword v137, v[22:23], off
	v_lshl_add_u64 v[22:23], v[22:23], 0, s[24:25]
	global_load_dword v138, v[22:23], off
	v_lshl_add_u64 v[22:23], v[22:23], 0, s[24:25]
	global_load_dword v139, v[22:23], off
	v_lshl_add_u64 v[22:23], v[22:23], 0, s[24:25]
	global_load_dword v140, v[22:23], off
	v_lshl_add_u64 v[22:23], v[22:23], 0, s[24:25]
	global_load_dword v141, v[22:23], off
	v_lshl_add_u64 v[22:23], v[22:23], 0, s[24:25]
	global_load_dword v142, v[22:23], off
	v_lshl_add_u64 v[22:23], v[22:23], 0, s[24:25]
	global_load_dword v143, v[22:23], off
	v_lshl_add_u64 v[22:23], v[22:23], 0, s[24:25]
	global_load_dword v144, v[22:23], off
	v_lshl_add_u64 v[22:23], v[22:23], 0, s[24:25]
	global_load_dword v145, v[22:23], off
	v_lshl_add_u64 v[22:23], v[22:23], 0, s[24:25]
	global_load_dword v146, v[22:23], off
	v_lshl_add_u64 v[22:23], v[22:23], 0, s[24:25]
	global_load_dword v147, v[22:23], off
	v_lshl_add_u64 v[22:23], v[22:23], 0, s[24:25]
	global_load_dword v148, v[22:23], off
	v_lshl_add_u64 v[22:23], v[22:23], 0, s[24:25]
	global_load_dword v149, v[22:23], off
	v_lshl_add_u64 v[22:23], v[22:23], 0, s[24:25]
	global_load_dword v150, v[22:23], off
	v_lshl_add_u64 v[22:23], v[22:23], 0, s[24:25]
	global_load_dword v151, v[22:23], off
	v_lshl_add_u64 v[22:23], v[22:23], 0, s[24:25]
	v_add_u32_e32 v21, s13, v9
	v_add_u32_e32 v24, 0x11000, v21
	ds_read_b128 v[160:163], v24
	ds_read_b128 v[164:167], v24 offset:8192
	ds_read_b128 v[168:171], v24 offset:16384
	ds_read_b128 v[172:175], v24 offset:24576
	ds_read_b128 v[176:179], v24 offset:32768
	s_waitcnt vmcnt(28) lgkmcnt(0)
	v_fmac_f32_e32 v14, v120, v160
	v_fmac_f32_e32 v15, v120, v164
	v_fmac_f32_e32 v16, v120, v168
	v_fmac_f32_e32 v17, v120, v172
	v_fmac_f32_e32 v20, v120, v176
	v_fmac_f32_e32 v14, v121, v161
	v_fmac_f32_e32 v15, v121, v165
	v_fmac_f32_e32 v16, v121, v169
	v_fmac_f32_e32 v17, v121, v173
	v_fmac_f32_e32 v20, v121, v177
	v_fmac_f32_e32 v14, v122, v162
	v_fmac_f32_e32 v15, v122, v166
	v_fmac_f32_e32 v16, v122, v170
	v_fmac_f32_e32 v17, v122, v174
	v_fmac_f32_e32 v20, v122, v178
	v_fmac_f32_e32 v14, v123, v163
	v_fmac_f32_e32 v15, v123, v167
	v_fmac_f32_e32 v16, v123, v171
	v_fmac_f32_e32 v17, v123, v175
	v_fmac_f32_e32 v20, v123, v179
	ds_read_b128 v[160:163], v24 offset:16
	ds_read_b128 v[164:167], v24 offset:8208
	ds_read_b128 v[168:171], v24 offset:16400
	ds_read_b128 v[172:175], v24 offset:24592
	ds_read_b128 v[176:179], v24 offset:32784
	s_waitcnt vmcnt(24) lgkmcnt(0)
	v_fmac_f32_e32 v14, v124, v160
	v_fmac_f32_e32 v15, v124, v164
	v_fmac_f32_e32 v16, v124, v168
	v_fmac_f32_e32 v17, v124, v172
	v_fmac_f32_e32 v20, v124, v176
	v_fmac_f32_e32 v14, v125, v161
	v_fmac_f32_e32 v15, v125, v165
	v_fmac_f32_e32 v16, v125, v169
	v_fmac_f32_e32 v17, v125, v173
	v_fmac_f32_e32 v20, v125, v177
	v_fmac_f32_e32 v14, v126, v162
	v_fmac_f32_e32 v15, v126, v166
	v_fmac_f32_e32 v16, v126, v170
	v_fmac_f32_e32 v17, v126, v174
	v_fmac_f32_e32 v20, v126, v178
	v_fmac_f32_e32 v14, v127, v163
	v_fmac_f32_e32 v15, v127, v167
	v_fmac_f32_e32 v16, v127, v171
	v_fmac_f32_e32 v17, v127, v175
	v_fmac_f32_e32 v20, v127, v179
	ds_read_b128 v[160:163], v24 offset:32
	ds_read_b128 v[164:167], v24 offset:8224
	ds_read_b128 v[168:171], v24 offset:16416
	ds_read_b128 v[172:175], v24 offset:24608
	ds_read_b128 v[176:179], v24 offset:32800
	s_waitcnt vmcnt(20) lgkmcnt(0)
; __global__ void __launch_bounds__(512, 2) mk_fwd(Args args) {
;     ...
;             for (int k = ksl * 256; k < ksl * 256 + 256; ++k) { const float w = wp[(size_t)k * 6144];
; #pragma unroll
;                 for (int r = 0; r < 5; ++r) a5[r] += sil[r * 2048 + k] * w; }
; #pragma unroll
;             for (int r = 0; r < 5; ++r) red[(ksl * 5 + r) * 64 + (tid & 63)] = a5[r];
;             __syncthreads();
;             if (tid < 320) { const int r = tid >> 6, cc = tid & 63; float s = 0.f;
; #pragma unroll
;                 for (int k = 0; k < 8; ++k) s += red[(k * 5 + r) * 64 + cc];
;                 MOD[((size_t)L * 5 + r) * 6144 + cb * 64 + cc] = s + ada_b[(size_t)L * 6144 + cb * 64 + cc]; }
	v_fmac_f32_e32 v14, v128, v160
	v_fmac_f32_e32 v15, v128, v164
	v_fmac_f32_e32 v16, v128, v168
	v_fmac_f32_e32 v17, v128, v172
	v_fmac_f32_e32 v20, v128, v176
	v_fmac_f32_e32 v14, v129, v161
	v_fmac_f32_e32 v15, v129, v165
	v_fmac_f32_e32 v16, v129, v169
	v_fmac_f32_e32 v17, v129, v173
	v_fmac_f32_e32 v20, v129, v177
	v_fmac_f32_e32 v14, v130, v162
	v_fmac_f32_e32 v15, v130, v166
	v_fmac_f32_e32 v16, v130, v170
	v_fmac_f32_e32 v17, v130, v174
	v_fmac_f32_e32 v20, v130, v178
	v_fmac_f32_e32 v14, v131, v163
	v_fmac_f32_e32 v15, v131, v167
	v_fmac_f32_e32 v16, v131, v171
	v_fmac_f32_e32 v17, v131, v175
	v_fmac_f32_e32 v20, v131, v179
	ds_read_b128 v[160:163], v24 offset:48
	ds_read_b128 v[164:167], v24 offset:8240
	ds_read_b128 v[168:171], v24 offset:16432
	ds_read_b128 v[172:175], v24 offset:24624
	ds_read_b128 v[176:179], v24 offset:32816
	s_waitcnt vmcnt(16) lgkmcnt(0)
	v_fmac_f32_e32 v14, v132, v160
	v_fmac_f32_e32 v15, v132, v164
	v_fmac_f32_e32 v16, v132, v168
	v_fmac_f32_e32 v17, v132, v172
	v_fmac_f32_e32 v20, v132, v176
	v_fmac_f32_e32 v14, v133, v161
	v_fmac_f32_e32 v15, v133, v165
	v_fmac_f32_e32 v16, v133, v169
	v_fmac_f32_e32 v17, v133, v173
	v_fmac_f32_e32 v20, v133, v177
	v_fmac_f32_e32 v14, v134, v162
	v_fmac_f32_e32 v15, v134, v166
	v_fmac_f32_e32 v16, v134, v170
	v_fmac_f32_e32 v17, v134, v174
	v_fmac_f32_e32 v20, v134, v178
	v_fmac_f32_e32 v14, v135, v163
	v_fmac_f32_e32 v15, v135, v167
	v_fmac_f32_e32 v16, v135, v171
	v_fmac_f32_e32 v17, v135, v175
	v_fmac_f32_e32 v20, v135, v179
	ds_read_b128 v[160:163], v24 offset:64
	ds_read_b128 v[164:167], v24 offset:8256
	ds_read_b128 v[168:171], v24 offset:16448
	ds_read_b128 v[172:175], v24 offset:24640
	ds_read_b128 v[176:179], v24 offset:32832
	s_waitcnt vmcnt(12) lgkmcnt(0)
	v_fmac_f32_e32 v14, v136, v160
	v_fmac_f32_e32 v15, v136, v164
	v_fmac_f32_e32 v16, v136, v168
	v_fmac_f32_e32 v17, v136, v172
	v_fmac_f32_e32 v20, v136, v176
	v_fmac_f32_e32 v14, v137, v161
	v_fmac_f32_e32 v15, v137, v165
	v_fmac_f32_e32 v16, v137, v169
	v_fmac_f32_e32 v17, v137, v173
	v_fmac_f32_e32 v20, v137, v177
	v_fmac_f32_e32 v14, v138, v162
	v_fmac_f32_e32 v15, v138, v166
	v_fmac_f32_e32 v16, v138, v170
	v_fmac_f32_e32 v17, v138, v174
	v_fmac_f32_e32 v20, v138, v178
	v_fmac_f32_e32 v14, v139, v163
	v_fmac_f32_e32 v15, v139, v167
	v_fmac_f32_e32 v16, v139, v171
	v_fmac_f32_e32 v17, v139, v175
	v_fmac_f32_e32 v20, v139, v179
	ds_read_b128 v[160:163], v24 offset:80
	ds_read_b128 v[164:167], v24 offset:8272
	ds_read_b128 v[168:171], v24 offset:16464
	ds_read_b128 v[172:175], v24 offset:24656
	ds_read_b128 v[176:179], v24 offset:32848
	s_waitcnt vmcnt(8) lgkmcnt(0)
	v_fmac_f32_e32 v14, v140, v160
	v_fmac_f32_e32 v15, v140, v164
	v_fmac_f32_e32 v16, v140, v168
	v_fmac_f32_e32 v17, v140, v172
	v_fmac_f32_e32 v20, v140, v176
	v_fmac_f32_e32 v14, v141, v161
	v_fmac_f32_e32 v15, v141, v165
	v_fmac_f32_e32 v16, v141, v169
	v_fmac_f32_e32 v17, v141, v173
	v_fmac_f32_e32 v20, v141, v177
	v_fmac_f32_e32 v14, v142, v162
	v_fmac_f32_e32 v15, v142, v166
	v_fmac_f32_e32 v16, v142, v170
	v_fmac_f32_e32 v17, v142, v174
	v_fmac_f32_e32 v20, v142, v178
	v_fmac_f32_e32 v14, v143, v163
	v_fmac_f32_e32 v15, v143, v167
	v_fmac_f32_e32 v16, v143, v171
	v_fmac_f32_e32 v17, v143, v175
	v_fmac_f32_e32 v20, v143, v179
	ds_read_b128 v[160:163], v24 offset:96
	ds_read_b128 v[164:167], v24 offset:8288
	ds_read_b128 v[168:171], v24 offset:16480
	ds_read_b128 v[172:175], v24 offset:24672
	ds_read_b128 v[176:179], v24 offset:32864
	s_waitcnt vmcnt(4) lgkmcnt(0)
	v_fmac_f32_e32 v14, v144, v160
	v_fmac_f32_e32 v15, v144, v164
	v_fmac_f32_e32 v16, v144, v168
	v_fmac_f32_e32 v17, v144, v172
	v_fmac_f32_e32 v20, v144, v176
	v_fmac_f32_e32 v14, v145, v161
	v_fmac_f32_e32 v15, v145, v165
	v_fmac_f32_e32 v16, v145, v169
	v_fmac_f32_e32 v17, v145, v173
	v_fmac_f32_e32 v20, v145, v177
	v_fmac_f32_e32 v14, v146, v162
	v_fmac_f32_e32 v15, v146, v166
	v_fmac_f32_e32 v16, v146, v170
	v_fmac_f32_e32 v17, v146, v174
	v_fmac_f32_e32 v20, v146, v178
	v_fmac_f32_e32 v14, v147, v163
	v_fmac_f32_e32 v15, v147, v167
	v_fmac_f32_e32 v16, v147, v171
	v_fmac_f32_e32 v17, v147, v175
	v_fmac_f32_e32 v20, v147, v179
	ds_read_b128 v[160:163], v24 offset:112
	ds_read_b128 v[164:167], v24 offset:8304
	ds_read_b128 v[168:171], v24 offset:16496
	ds_read_b128 v[172:175], v24 offset:24688
	ds_read_b128 v[176:179], v24 offset:32880
	s_waitcnt vmcnt(0) lgkmcnt(0)
	v_fmac_f32_e32 v14, v148, v160
	v_fmac_f32_e32 v15, v148, v164
	v_fmac_f32_e32 v16, v148, v168
	v_fmac_f32_e32 v17, v148, v172
	v_fmac_f32_e32 v20, v148, v176
	v_fmac_f32_e32 v14, v149, v161
	v_fmac_f32_e32 v15, v149, v165
	v_fmac_f32_e32 v16, v149, v169
	v_fmac_f32_e32 v17, v149, v173
	v_fmac_f32_e32 v20, v149, v177
	v_fmac_f32_e32 v14, v150, v162
	v_fmac_f32_e32 v15, v150, v166
	v_fmac_f32_e32 v16, v150, v170
	v_fmac_f32_e32 v17, v150, v174
	v_fmac_f32_e32 v20, v150, v178
	v_fmac_f32_e32 v14, v151, v163
	v_fmac_f32_e32 v15, v151, v167
	v_fmac_f32_e32 v16, v151, v171
	v_fmac_f32_e32 v17, v151, v175
	v_fmac_f32_e32 v20, v151, v179
	s_add_i32 s13, s13, 128
	s_cmpk_eq_i32 s13, 0x400
	s_cbranch_scc0 .Lada_kloop
	ds_write2st64_b32 v19, v14, v15 offset1:1
	ds_write2st64_b32 v19, v16, v17 offset0:2 offset1:3
	ds_write_b32 v19, v20 offset:1024
	s_waitcnt lgkmcnt(0)
	s_barrier
	s_and_saveexec_b64 s[0:1], s[2:3]
	s_cbranch_execz .LBB0_89
	s_ashr_i32 s13, s12, 31
	s_mul_i32 s23, s18, 0x6000
	s_mul_hi_i32 s19, s18, 0x6000
	s_add_u32 s23, s50, s23
	s_addc_u32 s19, s51, s19
	s_lshl_b64 s[12:13], s[12:13], 2
	s_add_u32 s24, s23, s12
	s_addc_u32 s25, s19, s13
	global_load_dword v26, v2, s[24:25]
	v_add_u32_e32 v24, v7, v1
	v_mad_i64_i32 v[12:13], s[18:19], s18, 5, v[10:11]
	v_mov_b64_e32 v[14:15], s[4:5]
	ds_read2st64_b32 v[16:17], v24 offset1:5
	ds_read2st64_b32 v[20:21], v24 offset0:10 offset1:15
	ds_read2st64_b32 v[22:23], v24 offset0:20 offset1:25
	ds_read2st64_b32 v[24:25], v24 offset0:30 offset1:35
	v_mad_u64_u32 v[14:15], s[18:19], v12, s14, v[14:15]
	v_mad_i32_i24 v15, v13, s14, v15
	v_lshl_add_u64 v[12:13], v[14:15], 0, s[12:13]
	s_waitcnt lgkmcnt(3)
	v_add_f32_e32 v14, 0, v16
	v_add_f32_e32 v14, v14, v17
	s_waitcnt lgkmcnt(2)
	v_add_f32_e32 v14, v14, v20
	v_add_f32_e32 v14, v14, v21
	s_waitcnt lgkmcnt(1)
	v_add_f32_e32 v14, v14, v22
	v_add_f32_e32 v14, v14, v23
	s_waitcnt lgkmcnt(0)
	v_add_f32_e32 v14, v14, v24
	v_add_f32_e32 v14, v14, v25
	v_lshl_add_u64 v[12:13], v[12:13], 0, v[2:3]
	s_waitcnt vmcnt(0)
	v_add_f32_e32 v14, v14, v26
	global_store_dword v[12:13], v14, off
	s_branch .LBB0_89

; __global__ void __launch_bounds__(512, 2) mk_fwd(Args args) {
;     ...
;         for (int row = gw; row < MROWS; row += NGW) {
;             const bool lat = row < NLAT;
;             const float* src = (layer == 0) ? (lat ? x_in + (size_t)row * DM : ctx_in + (size_t)(row - NLAT) * DM) : XCUR + (size_t)row * DM;
;             const float* mr = MOD + (size_t)layer * 5 * 6144 + (size_t)(lat ? (row >> 12) : 4) * 6144;
;             f32x4 v[8]; float ss = 0.f;
; #pragma unroll
;             for (int jv = 0; jv < 8; ++jv) { v[jv] = *(const f32x4*)(src + 4 * (lane + 64 * jv)); ss += (v[jv][0] * v[jv][0] + v[jv][1] * v[jv][1]) + (v[jv][2] * v[jv][2] + v[jv][3] * v[jv][3]); }
;             const float rinv = rsqrtf(wave_sum(ss, lane) * (1.f / DM) + EPS);
; #pragma unroll
;             for (int jv = 0; jv < 8; ++jv) { const int col = 4 * (lane + 64 * jv);
;                 const f32x4 gg = *(const f32x4*)(norm_g + layer * DM + col), sh = *(const f32x4*)(mr + col), sc = *(const f32x4*)(mr + 2048 + col);
.LBB0_122:
	s_min_i32 s28, s0, 0x4000
	s_ashr_i32 s28, s28, 12
	s_mul_hi_i32 s29, s28, 0x6000
	s_mulk_i32 s28, 0x6000
	s_add_u32 s28, s18, s28
	s_addc_u32 s29, s19, s29
	s_add_u32 s30, s28, 0x2000
	s_addc_u32 s31, s29, 0
	global_load_dwordx4 v[104:107], v[32:33], off
	global_load_dwordx4 v[108:111], v[32:33], off offset:1024
	global_load_dwordx4 v[112:115], v[32:33], off offset:2048
	global_load_dwordx4 v[116:119], v[32:33], off offset:3072
	global_load_dwordx4 v[120:123], v[34:35], off
	global_load_dwordx4 v[124:127], v[36:37], off
	global_load_dwordx4 v[128:131], v[38:39], off
	global_load_dwordx4 v[132:135], v[40:41], off
	global_load_dwordx4 v[136:139], v51, s[28:29]
	global_load_dwordx4 v[140:143], v51, s[28:29] offset:1024
	global_load_dwordx4 v[144:147], v51, s[28:29] offset:2048
	global_load_dwordx4 v[148:151], v51, s[28:29] offset:3072
	global_load_dwordx4 v[152:155], v52, s[28:29]
	global_load_dwordx4 v[156:159], v53, s[28:29]
	global_load_dwordx4 v[160:163], v54, s[28:29]
	global_load_dwordx4 v[164:167], v55, s[28:29]
	global_load_dwordx4 v[168:171], v51, s[30:31]
	global_load_dwordx4 v[172:175], v56, s[30:31]
	global_load_dwordx4 v[176:179], v57, s[30:31]
	global_load_dwordx4 v[180:183], v58, s[30:31]
	global_load_dwordx4 v[184:187], v52, s[30:31]
	global_load_dwordx4 v[188:191], v53, s[30:31]
	global_load_dwordx4 v[200:203], v54, s[30:31]
	global_load_dwordx4 v[204:207], v55, s[30:31]
	global_load_dwordx4 v[28:31], v51, s[10:11]
	global_load_dwordx4 v[0:3], v51, s[10:11] offset:1024
	global_load_dwordx4 v[12:15], v51, s[10:11] offset:2048
	global_load_dwordx4 v[208:211], v51, s[10:11] offset:3072
	global_load_dwordx4 v[212:215], v52, s[10:11]
	global_load_dwordx4 v[216:219], v53, s[10:11]
	global_load_dwordx4 v[220:223], v54, s[10:11]
	global_load_dwordx4 v[224:227], v55, s[10:11]
	s_min_i32 s12, s0, 0x4000
	s_ashr_i32 s13, s12, 12
	s_mul_hi_i32 s12, s13, 0x6000
	s_mulk_i32 s13, 0x6000
	s_waitcnt vmcnt(7)
	v_mov_b32_e32 v6, v29
	s_waitcnt vmcnt(6)
	v_mov_b32_e32 v7, v1
	v_mov_b32_e32 v4, v28
	v_mov_b32_e32 v5, v0
	v_pk_mul_f32 v[6:7], v[6:7], v[6:7]
	v_mov_b32_e32 v8, v31
	v_mov_b32_e32 v9, v3
	v_pk_fma_f32 v[4:5], v[4:5], v[4:5], v[6:7]
	v_mov_b32_e32 v6, v30
	v_mov_b32_e32 v7, v2
	v_pk_mul_f32 v[8:9], v[8:9], v[8:9]
	s_nop 0
	v_pk_fma_f32 v[6:7], v[6:7], v[6:7], v[8:9]
	s_nop 0
	v_pk_add_f32 v[16:17], v[4:5], v[6:7]
	s_waitcnt vmcnt(5)
	v_pk_mul_f32 v[4:5], v[14:15], v[14:15]
	v_pk_mul_f32 v[6:7], v[12:13], v[12:13]
	v_pk_add_f32 v[16:17], v[16:17], v[16:17] op_sel:[0,1] op_sel_hi:[1,0]
	v_pk_mov_b32 v[8:9], v[6:7], v[4:5] op_sel:[1,0]
	v_mov_b32_e32 v7, v5
	v_pk_add_f32 v[18:19], v[8:9], v[6:7]
	s_waitcnt vmcnt(2)
	v_mov_b64_e32 v[8:9], v[208:209]
	v_mov_b64_e32 v[10:11], v[210:211]
	v_mov_b64_e32 v[4:5], v[212:213]
	v_mov_b64_e32 v[6:7], v[214:215]
	v_mov_b64_e32 v[24:25], v[216:217]
	v_mov_b64_e32 v[26:27], v[218:219]
	v_pk_add_f32 v[18:19], v[18:19], v[18:19] op_sel:[0,1] op_sel_hi:[1,0]
	s_nop 0
	v_mul_f32_e32 v20, v4, v4
	v_mul_f32_e32 v21, v5, v5
	v_mov_b32_e32 v17, v20
	v_mov_b32_e32 v19, v21
	v_pk_add_f32 v[16:17], v[16:17], v[18:19]
	v_mul_f32_e32 v18, v9, v9
	v_mul_f32_e32 v20, v11, v11
	v_mul_f32_e32 v22, v6, v6
	v_mul_f32_e32 v23, v7, v7
	v_pk_fma_f32 v[18:19], v[8:9], v[8:9], v[18:19] op_sel_hi:[1,1,0]
	v_pk_fma_f32 v[20:21], v[10:11], v[10:11], v[20:21] op_sel_hi:[1,1,0]
	v_mov_b32_e32 v19, v22
	v_mov_b32_e32 v21, v23
	v_pk_add_f32 v[18:19], v[18:19], v[20:21]
	s_nop 0
	v_pk_add_f32 v[60:61], v[16:17], v[18:19]
	s_nop 0
	v_pk_mul_f32 v[16:17], v[26:27], v[26:27]
	v_pk_mul_f32 v[18:19], v[24:25], v[24:25]
	v_pk_add_f32 v[60:61], v[60:61], v[60:61] op_sel:[0,1] op_sel_hi:[1,0]
	v_pk_mov_b32 v[20:21], v[18:19], v[16:17] op_sel:[1,0]
	v_mov_b32_e32 v19, v17
	v_pk_add_f32 v[62:63], v[20:21], v[18:19]
	s_waitcnt vmcnt(0)
	v_mov_b64_e32 v[16:17], v[220:221]
	v_mov_b64_e32 v[18:19], v[222:223]
	v_mov_b64_e32 v[20:21], v[224:225]
	v_mov_b64_e32 v[22:23], v[226:227]
	v_pk_add_f32 v[62:63], v[62:63], v[62:63] op_sel:[0,1] op_sel_hi:[1,0]
	s_add_u32 s10, s18, s13
	s_addc_u32 s11, s19, s12
	s_add_u32 s12, s10, 0x2000
	s_addc_u32 s13, s11, 0
	s_lshl_b64 s[14:15], s[14:15], 12
	s_add_u32 s0, s0, s2
	s_addc_u32 s1, s1, s3
	s_add_u32 s6, s6, s8
	s_addc_u32 s7, s7, s9
	s_cmpk_gt_i32 s0, 0x43ff
	s_waitcnt vmcnt(0)
	v_mul_f32_e32 v44, v20, v20
	v_mul_f32_e32 v59, v21, v21
	v_mov_b32_e32 v61, v44
	v_mov_b32_e32 v63, v59
	v_mul_f32_e32 v44, v17, v17
	v_mul_f32_e32 v64, v22, v22
	v_pk_add_f32 v[60:61], v[60:61], v[62:63]
	v_pk_fma_f32 v[62:63], v[16:17], v[16:17], v[44:45] op_sel_hi:[1,1,0]
	v_mul_f32_e32 v44, v19, v19
	v_mul_f32_e32 v66, v23, v23
	v_mov_b32_e32 v63, v64
	v_pk_fma_f32 v[64:65], v[18:19], v[18:19], v[44:45] op_sel_hi:[1,1,0]
	s_nop 0
	v_mov_b32_e32 v65, v66
	v_pk_add_f32 v[62:63], v[62:63], v[64:65]
	s_nop 0
	v_pk_add_f32 v[60:61], v[60:61], v[62:63]
	s_nop 0
	v_add_f32_e32 v44, v60, v61
	s_nop 0
	ds_bpermute_b32 v59, v45, v44
	s_waitcnt lgkmcnt(0)
	v_add_f32_e32 v44, v44, v59
	ds_bpermute_b32 v59, v46, v44
	s_waitcnt lgkmcnt(0)
	v_add_f32_e32 v44, v44, v59
	ds_bpermute_b32 v59, v47, v44
	s_waitcnt lgkmcnt(0)
; __device__ __forceinline__ unsigned cvt_pk(float lo, float hi) { f32x2_t v = {lo, hi}; bf16x2_t b = __builtin_convertvector(v, bf16x2_t); return __builtin_bit_cast(unsigned, b); }
; __global__ void __launch_bounds__(512, 2) mk_fwd(Args args) {
;     ...
;             const float rinv = rsqrtf(wave_sum(ss, lane) * (1.f / DM) + EPS);
; #pragma unroll
;             for (int jv = 0; jv < 8; ++jv) { const int col = 4 * (lane + 64 * jv);
;                 const f32x4 gg = *(const f32x4*)(norm_g + layer * DM + col), sh = *(const f32x4*)(mr + col), sc = *(const f32x4*)(mr + 2048 + col);
;                 const f32x4 hh = (v[jv] * rinv * gg) * (sc + 1.f) + sh;
;                 u32x2 w; w.x = cvt_pk(hh[0], hh[1]); w.y = cvt_pk(hh[2], hh[3]); *(u32x2*)(HB + (size_t)row * DM + col) = w; }
	v_add_f32_e32 v44, v44, v59
	ds_bpermute_b32 v59, v48, v44
	s_waitcnt lgkmcnt(0)
	v_add_f32_e32 v44, v44, v59
	ds_bpermute_b32 v59, v49, v44
	s_waitcnt lgkmcnt(0)
	v_add_f32_e32 v44, v44, v59
	ds_bpermute_b32 v59, v50, v44
	s_waitcnt lgkmcnt(0)
	v_add_f32_e32 v44, v44, v59
	v_fmamk_f32 v44, v44, 0x3a000000, v250
	v_cmp_gt_f32_e32 vcc, s61, v44
	v_mul_f32_e32 v59, 0x4b800000, v44
	s_nop 0
	v_cndmask_b32_e32 v44, v44, v59, vcc
	v_rsq_f32_e32 v44, v44
	s_nop 0
	v_mul_f32_e32 v59, 0x45800000, v44
	v_cndmask_b32_e32 v44, v44, v59, vcc
	v_pk_mul_f32 v[30:31], v[44:45], v[30:31] op_sel_hi:[0,1]
	v_pk_mul_f32 v[28:29], v[44:45], v[28:29] op_sel_hi:[0,1]
	v_pk_mul_f32 v[2:3], v[44:45], v[2:3] op_sel_hi:[0,1]
	v_pk_mul_f32 v[0:1], v[44:45], v[0:1] op_sel_hi:[0,1]
	v_pk_mul_f32 v[14:15], v[44:45], v[14:15] op_sel_hi:[0,1]
	v_pk_mul_f32 v[12:13], v[44:45], v[12:13] op_sel_hi:[0,1]
	v_pk_mul_f32 v[10:11], v[44:45], v[10:11] op_sel_hi:[0,1]
	v_pk_mul_f32 v[8:9], v[44:45], v[8:9] op_sel_hi:[0,1]
	v_pk_mul_f32 v[6:7], v[44:45], v[6:7] op_sel_hi:[0,1]
	v_pk_mul_f32 v[4:5], v[44:45], v[4:5] op_sel_hi:[0,1]
	v_lshl_add_u64 v[84:85], v[42:43], 0, s[14:15]
	v_pk_mul_f32 v[28:29], v[104:105], v[28:29]
	v_pk_mul_f32 v[30:31], v[106:107], v[30:31]
	v_pk_add_f32 v[170:171], v[170:171], 1.0 op_sel_hi:[1,0]
	v_pk_add_f32 v[168:169], v[168:169], 1.0 op_sel_hi:[1,0]
	v_pk_fma_f32 v[30:31], v[170:171], v[30:31], v[138:139]
	v_pk_fma_f32 v[28:29], v[168:169], v[28:29], v[136:137]
	s_nop 0
	v_cvt_pk_bf16_f32 v28, v28, v29
	v_cvt_pk_bf16_f32 v29, v30, v31
	global_store_dwordx2 v[84:85], v[28:29], off
	v_pk_mul_f32 v[0:1], v[108:109], v[0:1]
	v_pk_mul_f32 v[2:3], v[110:111], v[2:3]
	v_pk_add_f32 v[174:175], v[174:175], 1.0 op_sel_hi:[1,0]
	v_pk_add_f32 v[172:173], v[172:173], 1.0 op_sel_hi:[1,0]
	v_pk_fma_f32 v[2:3], v[174:175], v[2:3], v[142:143]
	v_pk_fma_f32 v[0:1], v[172:173], v[0:1], v[140:141]
	s_nop 0
	v_cvt_pk_bf16_f32 v0, v0, v1
	v_cvt_pk_bf16_f32 v1, v2, v3
	global_store_dwordx2 v[84:85], v[0:1], off offset:512
	v_pk_mul_f32 v[12:13], v[112:113], v[12:13]
	v_pk_mul_f32 v[14:15], v[114:115], v[14:15]
	v_pk_add_f32 v[178:179], v[178:179], 1.0 op_sel_hi:[1,0]
	v_pk_add_f32 v[176:177], v[176:177], 1.0 op_sel_hi:[1,0]
	v_pk_fma_f32 v[14:15], v[178:179], v[14:15], v[146:147]
	v_pk_fma_f32 v[12:13], v[176:177], v[12:13], v[144:145]
	s_nop 0
	v_cvt_pk_bf16_f32 v12, v12, v13
	v_cvt_pk_bf16_f32 v13, v14, v15
	global_store_dwordx2 v[84:85], v[12:13], off offset:1024
	v_pk_mul_f32 v[8:9], v[116:117], v[8:9]
	v_pk_mul_f32 v[10:11], v[118:119], v[10:11]
	v_pk_add_f32 v[182:183], v[182:183], 1.0 op_sel_hi:[1,0]
	v_pk_add_f32 v[180:181], v[180:181], 1.0 op_sel_hi:[1,0]
	v_pk_fma_f32 v[10:11], v[182:183], v[10:11], v[150:151]
	v_pk_fma_f32 v[8:9], v[180:181], v[8:9], v[148:149]
	s_nop 0
	v_cvt_pk_bf16_f32 v8, v8, v9
	v_cvt_pk_bf16_f32 v9, v10, v11
	global_store_dwordx2 v[84:85], v[8:9], off offset:1536
	v_pk_mul_f32 v[4:5], v[120:121], v[4:5]
	v_pk_mul_f32 v[6:7], v[122:123], v[6:7]
	v_pk_add_f32 v[186:187], v[186:187], 1.0 op_sel_hi:[1,0]
	v_pk_add_f32 v[184:185], v[184:185], 1.0 op_sel_hi:[1,0]
	v_pk_fma_f32 v[6:7], v[186:187], v[6:7], v[154:155]
	v_pk_fma_f32 v[4:5], v[184:185], v[4:5], v[152:153]
	s_nop 0
	v_cvt_pk_bf16_f32 v4, v4, v5
	v_cvt_pk_bf16_f32 v5, v6, v7
	global_store_dwordx2 v[84:85], v[4:5], off offset:2048
	v_pk_mul_f32 v[24:25], v[44:45], v[24:25] op_sel_hi:[0,1]
	v_pk_mul_f32 v[26:27], v[44:45], v[26:27] op_sel_hi:[0,1]
	v_pk_mul_f32 v[24:25], v[124:125], v[24:25]
	v_pk_mul_f32 v[26:27], v[126:127], v[26:27]
	v_pk_add_f32 v[190:191], v[190:191], 1.0 op_sel_hi:[1,0]
	v_pk_add_f32 v[188:189], v[188:189], 1.0 op_sel_hi:[1,0]
	v_pk_fma_f32 v[26:27], v[190:191], v[26:27], v[158:159]
	v_pk_fma_f32 v[24:25], v[188:189], v[24:25], v[156:157]
	s_nop 0
	v_cvt_pk_bf16_f32 v24, v24, v25
	v_cvt_pk_bf16_f32 v25, v26, v27
	global_store_dwordx2 v[84:85], v[24:25], off offset:2560
	v_pk_mul_f32 v[16:17], v[44:45], v[16:17] op_sel_hi:[0,1]
	v_pk_mul_f32 v[18:19], v[44:45], v[18:19] op_sel_hi:[0,1]
	v_pk_mul_f32 v[16:17], v[128:129], v[16:17]
	v_pk_mul_f32 v[18:19], v[130:131], v[18:19]
	v_pk_add_f32 v[202:203], v[202:203], 1.0 op_sel_hi:[1,0]
	v_pk_add_f32 v[200:201], v[200:201], 1.0 op_sel_hi:[1,0]
	v_pk_fma_f32 v[18:19], v[202:203], v[18:19], v[162:163]
	v_pk_fma_f32 v[16:17], v[200:201], v[16:17], v[160:161]
	s_nop 0
	v_cvt_pk_bf16_f32 v16, v16, v17
	v_cvt_pk_bf16_f32 v17, v18, v19
	global_store_dwordx2 v[84:85], v[16:17], off offset:3072
	v_pk_mul_f32 v[20:21], v[44:45], v[20:21] op_sel_hi:[0,1]
	v_pk_mul_f32 v[22:23], v[44:45], v[22:23] op_sel_hi:[0,1]
	v_pk_mul_f32 v[20:21], v[132:133], v[20:21]
	v_pk_mul_f32 v[22:23], v[134:135], v[22:23]
	v_pk_add_f32 v[206:207], v[206:207], 1.0 op_sel_hi:[1,0]
	v_pk_add_f32 v[204:205], v[204:205], 1.0 op_sel_hi:[1,0]
	v_pk_fma_f32 v[22:23], v[206:207], v[22:23], v[166:167]
	v_pk_fma_f32 v[20:21], v[204:205], v[20:21], v[164:165]
	s_nop 0
	v_cvt_pk_bf16_f32 v20, v20, v21
	v_cvt_pk_bf16_f32 v21, v22, v23
	global_store_dwordx2 v[84:85], v[20:21], off offset:3584
	s_cbranch_scc1 .LBB0_128

; #define LAS __attribute__((address_space(3)))
; __device__ __forceinline__ void na_item(const bf16_t* __restrict__ PMIX, const bf16_t* __restrict__ GP, bf16_t* __restrict__ O, const float* __restrict__ bias, int item, int lane, LAS unsigned char* wl) {
;     const int q = lane & 31, hi = lane >> 5;
;     const bool lat = item < 8192;
;     int b, h, gi = 0, jh = 0, qrow;
;     if (lat) { b = item >> 11; h = (item >> 7) & 15; gi = (item >> 1) & 63; jh = item & 1; qrow = b * 4096 + gi * 64 + jh * 32 + q; }
;     else { const int it = item - 8192; b = it >> 7; h = (it >> 3) & 15; qrow = NLAT + b * 256 + (it & 7) * 32 + q; }
;     const int j = jh * 32 + q;
;     const int c0 = min(max(j - 8, 0), 48), r0 = min(max(gi - 4, 0), 56);
;     const bf16_t* qp = PMIX + (size_t)qrow * NMIXP + O_NAQ + h * 64 + hi * 8;
;     bf16x8 qf[4];
; #pragma unroll
;     for (int ks = 0; ks < 4; ++ks) qf[ks] = *reinterpret_cast<const bf16x8*>(qp + ks * 16);
;     f32x16 oT0 = {}, oT1 = {}; float m = -1e30f, l = 0.f;
;     const int ntiles = lat ? 24 : 8;
;     const float* bh = bias + h * (15 * 31);
;     LAS float* lbias = (LAS float*)(wl + 4608);
;     if (lat) {
; #pragma unroll
;         for (int i = 0; i < 4; ++i) { const int e = lane * 4 + i, krr = e >> 5, dc = e & 31; lbias[e] = bh[(r0 + krr - gi + 7) * 31 + min(dc, 30)] * LOG2E; }
;         asm volatile("s_waitcnt vmcnt(0) lgkmcnt(0)" ::: "memory"); __builtin_amdgcn_wave_barrier();
;     }
; __global__ void __launch_bounds__(512, 2) mk_fwd(Args args) {
;     ...
;             const int nna = 8192 + (need_ctx ? 512 : 0);
;             for (int it = gw; it < nna; it += NGW) na_item(PMIX, GP, OB, rel_bias + (size_t)layer * 16 * 15 * 31, it, lane, lds + wid * 5632);
.LBB0_593:
	s_ashr_i32 s0, s19, 6
	s_lshl_b32 s1, s91, 3
	s_add_i32 s78, s1, s0
	s_cmpk_eq_i32 s89, 0x100
	s_cbranch_scc0 .Lna_norot
	s_addk_i32 s78, 0x600
	s_and_b32 s78, s78, 0x7ff
.Lna_norot:
	v_writelane_b32 v255, s34, 38
	s_and_b64 s[2:3], s[34:35], exec
	s_movk_i32 s1, 0x2200
	s_cselect_b32 s79, s1, 0x2000
	v_writelane_b32 v255, s35, 39
	s_cmp_ge_i32 s78, s79
	s_barrier
	s_cbranch_scc1 .LBB0_625
	s_lshl_b32 s80, s89, 3
	s_add_u32 s74, s90, 0x2087a000
	v_readlane_b32 s1, v255, 37
	s_addc_u32 s75, s1, 0
	s_add_u32 s2, s90, 0x2b27a000
	s_addc_u32 s3, s1, 0
	v_readlane_b32 s8, v254, 18
	s_add_u32 s4, s90, 0x572a6000
	v_readlane_b32 s6, v255, 20
	v_readlane_b32 s9, v254, 19
	v_readlane_b32 s10, v254, 20
	v_readlane_b32 s11, v254, 21
	v_readlane_b32 s12, v254, 22
	v_readlane_b32 s13, v254, 23
	v_readlane_b32 s16, v254, 26
	v_readlane_b32 s17, v254, 27
	s_addc_u32 s5, s1, 0
	s_mul_hi_u32 s1, s6, 0x7440
	s_mulk_i32 s6, 0x7440
	v_readlane_b32 s18, v254, 28
	v_readlane_b32 s19, v254, 29
	v_readlane_b32 s20, v254, 30
	v_readlane_b32 s21, v254, 31
	s_mov_b64 s[8:9], s[16:17]
	s_add_u32 s6, s8, s6
	s_mulk_i32 s0, 0x1600
	v_and_b32_e32 v0, 63, v176
	s_addc_u32 s82, s9, s1
	s_add_i32 s88, s0, 0
	v_bfe_u32 v1, v176, 5, 1
	v_lshlrev_b32_e32 v2, 2, v0
	v_mov_b32_e32 v3, s88
	v_bfe_u32 v167, v176, 1, 5
	s_movk_i32 s0, 0x90
	v_lshlrev_b32_e32 v168, 2, v1
	v_and_b32_e32 v128, 28, v2
	v_mad_u32_u24 v5, v167, s0, v3
	v_xor_b32_e32 v169, 0x80, v2
	v_or_b32_e32 v133, 8, v168
	v_lshlrev_b32_e32 v2, 4, v1
	v_mov_b32_e32 v3, v195
	v_or_b32_e32 v132, 32, v168
	v_lshl_add_u64 v[142:143], s[74:75], 0, v[2:3]
	v_lshlrev_b32_e32 v2, 1, v133
	v_and_b32_e32 v164, 31, v176
	v_lshl_add_u32 v166, v0, 4, s88
	v_or_b32_e32 v0, 3, v128
	v_and_b32_e32 v4, 1, v176
	v_or_b32_e32 v136, 40, v168
	v_lshl_add_u64 v[148:149], s[2:3], 0, v[2:3]
	v_lshl_add_u64 v[150:151], s[4:5], 0, v[2:3]
	v_lshlrev_b32_e32 v2, 1, v132
	v_lshlrev_b32_e32 v194, 3, v1
	v_min_u32_e32 v130, 30, v0
	v_lshlrev_b32_e32 v0, 5, v4
	v_lshlrev_b32_e32 v4, 6, v4
	v_lshl_add_u32 v6, v164, 1, s88
	v_mul_u32_u24_e32 v7, 0x240, v1
	v_mul_u32_u24_e32 v8, 0x90, v133
	v_lshl_add_u64 v[152:153], s[2:3], 0, v[2:3]
	v_lshl_add_u64 v[154:155], s[4:5], 0, v[2:3]
	v_lshlrev_b32_e32 v2, 1, v136
	v_readlane_b32 s7, v255, 21
	v_writelane_b32 v255, s6, 40
	v_bfe_u32 v165, v176, 3, 3
	v_or_b32_e32 v170, 16, v168
	v_or_b32_e32 v171, 17, v168
	v_or_b32_e32 v172, 18, v168
	v_or_b32_e32 v173, 19, v168
	v_or_b32_e32 v174, 24, v168
	v_or_b32_e32 v175, 25, v168
	v_or_b32_e32 v176, 26, v168
	v_or_b32_e32 v177, 27, v168
	v_or_b32_e32 v135, 33, v168
	v_or_b32_e32 v137, 35, v168
	v_or_b32_e32 v134, 34, v168
	v_or_b32_e32 v139, 41, v168
	v_or_b32_e32 v141, 43, v168
	v_or_b32_e32 v138, 42, v168
	v_mov_b32_e32 v129, v195
	v_mov_b32_e32 v131, v195
	v_lshl_add_u64 v[144:145], s[2:3], 0, v[194:195]
	v_lshl_add_u64 v[146:147], s[4:5], 0, v[194:195]
	v_lshl_add_u64 v[156:157], s[2:3], 0, v[2:3]
	v_lshl_add_u64 v[158:159], s[4:5], 0, v[2:3]
	v_or_b32_e32 v178, 0x48, v168
	v_add_u32_e32 v179, 0x47, v168
	v_or_b32_e32 v180, 0x42, v168
	v_or_b32_e32 v181, 0x41, v168
	v_or_b32_e32 v182, 64, v168
	v_add_u32_e32 v183, 63, v168
	v_lshlrev_b32_e32 v160, 1, v194
	v_lshlrev_b32_e32 v194, 1, v0
	v_add_u32_e32 v184, v5, v4
	v_add_u32_e32 v185, v6, v7
	v_add_u32_e32 v186, v6, v8
	v_bfe_u32 v229, v164, 2, 2
	v_mul_u32_u24_e32 v229, 0x90, v229
	v_bfe_u32 v253, v164, 4, 1
	v_lshl_add_u32 v229, v253, 5, v229
	v_and_b32_e32 v253, 3, v164
	v_lshl_add_u32 v229, v253, 3, v229
	v_add_u32_e32 v229, v229, v7
	v_add_u32_e32 v229, s88, v229
	v_readlane_b32 s14, v254, 24
	v_readlane_b32 s15, v254, 25
	v_readlane_b32 s22, v254, 32
	v_readlane_b32 s23, v254, 33
	s_mov_b64 s[10:11], s[18:19]
	s_mov_b64 s[12:13], s[20:21]
	s_branch .LBB0_596
; __device__ __forceinline__ unsigned cvt_pk(float lo, float hi) { f32x2_t v = {lo, hi}; bf16x2_t b = __builtin_convertvector(v, bf16x2_t); return __builtin_bit_cast(unsigned, b); }
; __device__ __forceinline__ float bflo(unsigned u) { return __uint_as_float(u << 16); }
; __device__ __forceinline__ float bfhi(unsigned u) { return __uint_as_float(u & 0xffff0000u); }
; __device__ __forceinline__ float shx(float v, int lane, int m) { return __int_as_float(__builtin_amdgcn_ds_bpermute((lane ^ m) << 2, __float_as_int(v))); }
; __device__ __forceinline__ void na_item(const bf16_t* __restrict__ PMIX, const bf16_t* __restrict__ GP, bf16_t* __restrict__ O, const float* __restrict__ bias, int item, int lane, LAS unsigned char* wl) {
;     ...
;     const float inv = __builtin_amdgcn_rcpf(l + shx(l, lane, 32));
;     const size_t ob = (size_t)qrow * 3072 + 1024 + h * 64;
; #pragma unroll
;     for (int db = 0; db < 2; ++db)
; #pragma unroll
;         for (int g = 0; g < 4; ++g) {
;             const int d = 32 * db + 8 * g + 4 * hi;
;             const u32x2 gw = *reinterpret_cast<const u32x2*>(GP + ob + d);
;             float v0, v1, v2, v3;
;             if (db == 0) { v0 = oT0[4 * g]; v1 = oT0[4 * g + 1]; v2 = oT0[4 * g + 2]; v3 = oT0[4 * g + 3]; } else { v0 = oT1[4 * g]; v1 = oT1[4 * g + 1]; v2 = oT1[4 * g + 2]; v3 = oT1[4 * g + 3]; }
;             u32x2 w; w.x = cvt_pk(v0 * inv * bflo(gw.x), v1 * inv * bfhi(gw.x)); w.y = cvt_pk(v2 * inv * bflo(gw.y), v3 * inv * bfhi(gw.y));
;             *reinterpret_cast<u32x2*>(O + ob + d) = w;
;         }
.LBB0_595:
	s_movk_i32 s66, 0xc00
	v_mad_i64_i32 v[34:35], s[0:1], v187, s66, 0
	v_or_b32_e32 v34, s85, v34
	v_mov_b64_e32 v[36:37], 0x800
	v_lshl_add_u64 v[36:37], v[34:35], 1, v[36:37]
	v_lshl_add_u64 v[34:35], v[144:145], 0, v[36:37]
	global_load_dwordx2 v[38:39], v[34:35], off
	ds_bpermute_b32 v32, v169, v232
	s_add_i32 s78, s78, s80
	v_readlane_b32 s62, v255, 24
	v_readlane_b32 s38, v255, 26
	v_readlane_b32 s36, v255, 28
	s_waitcnt lgkmcnt(0)
	v_add_f32_e32 v32, v232, v32
	v_rcp_f32_e32 v32, v32
	v_readlane_b32 s42, v255, 30
	s_cmp_ge_i32 s78, s79
	v_readlane_b32 s0, v254, 34
	v_pk_mul_f32 v[16:17], v[16:17], v[32:33] op_sel_hi:[1,0]
	v_pk_mul_f32 v[20:21], v[20:21], v[32:33] op_sel_hi:[1,0]
	v_pk_mul_f32 v[0:1], v[0:1], v[32:33] op_sel_hi:[1,0]
	v_pk_mul_f32 v[2:3], v[2:3], v[32:33] op_sel_hi:[1,0]
	v_readlane_b32 s63, v255, 25
	v_readlane_b32 s39, v255, 27
	v_readlane_b32 s37, v255, 29
	v_readlane_b32 s43, v255, 31
	s_movk_i32 s93, 0x100
	s_mov_b32 s61, 0x800000
	s_movk_i32 s64, 0x3000
	s_movk_i32 s65, 0x7e0
	v_readlane_b32 s1, v254, 35
	v_readlane_b32 s2, v254, 36
	v_readlane_b32 s3, v254, 37
	v_readlane_b32 s4, v254, 38
	v_readlane_b32 s5, v254, 39
	v_readlane_b32 s6, v254, 40
	v_readlane_b32 s7, v254, 41
	v_readlane_b32 s8, v254, 42
	v_readlane_b32 s9, v254, 43
	v_readlane_b32 s10, v254, 44
	v_readlane_b32 s11, v254, 45
	v_readlane_b32 s12, v254, 46
	v_readlane_b32 s13, v254, 47
	v_readlane_b32 s14, v254, 48
	v_readlane_b32 s15, v254, 49
	global_load_dwordx2 v[40:41], v[34:35], off offset:16
	global_load_dwordx2 v[42:43], v[34:35], off offset:32
	global_load_dwordx2 v[44:45], v[34:35], off offset:48
	global_load_dwordx2 v[46:47], v[34:35], off offset:64
	global_load_dwordx2 v[48:49], v[34:35], off offset:80
	global_load_dwordx2 v[50:51], v[34:35], off offset:96
	global_load_dwordx2 v[52:53], v[34:35], off offset:112
	v_lshl_add_u64 v[54:55], v[146:147], 0, v[36:37]
	v_pk_mul_f32 v[18:19], v[18:19], v[32:33] op_sel_hi:[1,0]
	v_pk_mul_f32 v[22:23], v[22:23], v[32:33] op_sel_hi:[1,0]
	v_pk_mul_f32 v[24:25], v[24:25], v[32:33] op_sel_hi:[1,0]
	v_pk_mul_f32 v[26:27], v[26:27], v[32:33] op_sel_hi:[1,0]
	v_pk_mul_f32 v[28:29], v[28:29], v[32:33] op_sel_hi:[1,0]
	v_pk_mul_f32 v[30:31], v[30:31], v[32:33] op_sel_hi:[1,0]
	v_pk_mul_f32 v[4:5], v[4:5], v[32:33] op_sel_hi:[1,0]
	v_pk_mul_f32 v[6:7], v[6:7], v[32:33] op_sel_hi:[1,0]
	v_pk_mul_f32 v[8:9], v[8:9], v[32:33] op_sel_hi:[1,0]
	v_pk_mul_f32 v[10:11], v[10:11], v[32:33] op_sel_hi:[1,0]
	v_pk_mul_f32 v[12:13], v[12:13], v[32:33] op_sel_hi:[1,0]
	v_pk_mul_f32 v[14:15], v[14:15], v[32:33] op_sel_hi:[1,0]
	s_waitcnt vmcnt(7)
	v_lshlrev_b32_e32 v56, 16, v38
	v_and_b32_e32 v57, 0xffff0000, v38
	v_lshlrev_b32_e32 v58, 16, v39
	v_and_b32_e32 v59, 0xffff0000, v39
	v_pk_mul_f32 v[16:17], v[16:17], v[56:57]
	v_pk_mul_f32 v[18:19], v[18:19], v[58:59]
	s_nop 0
	v_cvt_pk_bf16_f32 v38, v16, v17
	v_cvt_pk_bf16_f32 v39, v18, v19
	global_store_dwordx2 v[54:55], v[38:39], off
	s_waitcnt vmcnt(7)
	v_lshlrev_b32_e32 v56, 16, v40
	v_and_b32_e32 v57, 0xffff0000, v40
	v_lshlrev_b32_e32 v58, 16, v41
	v_and_b32_e32 v59, 0xffff0000, v41
	v_pk_mul_f32 v[20:21], v[20:21], v[56:57]
	v_pk_mul_f32 v[22:23], v[22:23], v[58:59]
	s_nop 0
	v_cvt_pk_bf16_f32 v40, v20, v21
	v_cvt_pk_bf16_f32 v41, v22, v23
	global_store_dwordx2 v[54:55], v[40:41], off offset:16
	s_waitcnt vmcnt(7)
	v_lshlrev_b32_e32 v56, 16, v42
	v_and_b32_e32 v57, 0xffff0000, v42
	v_lshlrev_b32_e32 v58, 16, v43
	v_and_b32_e32 v59, 0xffff0000, v43
	v_pk_mul_f32 v[24:25], v[24:25], v[56:57]
	v_pk_mul_f32 v[26:27], v[26:27], v[58:59]
	s_nop 0
	v_cvt_pk_bf16_f32 v42, v24, v25
	v_cvt_pk_bf16_f32 v43, v26, v27
	global_store_dwordx2 v[54:55], v[42:43], off offset:32
	s_waitcnt vmcnt(7)
	v_lshlrev_b32_e32 v56, 16, v44
	v_and_b32_e32 v57, 0xffff0000, v44
	v_lshlrev_b32_e32 v58, 16, v45
	v_and_b32_e32 v59, 0xffff0000, v45
	v_pk_mul_f32 v[28:29], v[28:29], v[56:57]
	v_pk_mul_f32 v[30:31], v[30:31], v[58:59]
	s_nop 0
	v_cvt_pk_bf16_f32 v44, v28, v29
	v_cvt_pk_bf16_f32 v45, v30, v31
	global_store_dwordx2 v[54:55], v[44:45], off offset:48
	s_waitcnt vmcnt(7)
	v_lshlrev_b32_e32 v56, 16, v46
	v_and_b32_e32 v57, 0xffff0000, v46
	v_lshlrev_b32_e32 v58, 16, v47
	v_and_b32_e32 v59, 0xffff0000, v47
	v_pk_mul_f32 v[0:1], v[0:1], v[56:57]
	v_pk_mul_f32 v[2:3], v[2:3], v[58:59]
	s_nop 0
	v_cvt_pk_bf16_f32 v46, v0, v1
	v_cvt_pk_bf16_f32 v47, v2, v3
	global_store_dwordx2 v[54:55], v[46:47], off offset:64
	s_waitcnt vmcnt(7)
	v_lshlrev_b32_e32 v56, 16, v48
	v_and_b32_e32 v57, 0xffff0000, v48
	v_lshlrev_b32_e32 v58, 16, v49
	v_and_b32_e32 v59, 0xffff0000, v49
	v_pk_mul_f32 v[4:5], v[4:5], v[56:57]
	v_pk_mul_f32 v[6:7], v[6:7], v[58:59]
	s_nop 0
	v_cvt_pk_bf16_f32 v48, v4, v5
	v_cvt_pk_bf16_f32 v49, v6, v7
	global_store_dwordx2 v[54:55], v[48:49], off offset:80
	s_waitcnt vmcnt(7)
	v_lshlrev_b32_e32 v56, 16, v50
	v_and_b32_e32 v57, 0xffff0000, v50
	v_lshlrev_b32_e32 v58, 16, v51
	v_and_b32_e32 v59, 0xffff0000, v51
	v_pk_mul_f32 v[8:9], v[8:9], v[56:57]
	v_pk_mul_f32 v[10:11], v[10:11], v[58:59]
	s_nop 0
	v_cvt_pk_bf16_f32 v50, v8, v9
	v_cvt_pk_bf16_f32 v51, v10, v11
	global_store_dwordx2 v[54:55], v[50:51], off offset:96
	s_waitcnt vmcnt(7)
	v_lshlrev_b32_e32 v56, 16, v52
	v_and_b32_e32 v57, 0xffff0000, v52
	v_lshlrev_b32_e32 v58, 16, v53
	v_and_b32_e32 v59, 0xffff0000, v53
	v_pk_mul_f32 v[12:13], v[12:13], v[56:57]
	v_pk_mul_f32 v[14:15], v[14:15], v[58:59]
	s_nop 0
	v_cvt_pk_bf16_f32 v52, v12, v13
	v_cvt_pk_bf16_f32 v53, v14, v15
	global_store_dwordx2 v[54:55], v[52:53], off offset:112
	s_cbranch_scc1 .LBB0_625

.LBB0_610:
	v_add_f32_e32 v222, 0, v234
	v_add_f32_e32 v222, v235, v222
	v_add_f32_e32 v222, v236, v222
	v_add_f32_e32 v222, v237, v222
	v_add_f32_e32 v222, v238, v222
	v_add_f32_e32 v222, v239, v222
	v_add_f32_e32 v222, v240, v222
	v_add_f32_e32 v222, v241, v222
	v_add_f32_e32 v222, v242, v222
	v_add_f32_e32 v222, v243, v222
	v_add_f32_e32 v222, v244, v222
	v_add_f32_e32 v222, v245, v222
	v_add_f32_e32 v222, v246, v222
	v_add_f32_e32 v222, v247, v222
	v_add_f32_e32 v222, v248, v222
	v_add_f32_e32 v234, v249, v222
	v_fmac_f32_e32 v234, v232, v140
	v_max_f32_e32 v140, v33, v33
	v_max_f32_e32 v222, v32, v32
	v_max_f32_e32 v140, v222, v140
	v_max3_f32 v140, v140, v34, v35
	v_max3_f32 v140, v140, v36, v37
	v_max3_f32 v140, v140, v38, v39
	v_max3_f32 v140, v140, v40, v41
	v_max3_f32 v140, v140, v42, v43
	v_max3_f32 v140, v140, v44, v45
	v_max3_f32 v140, v140, v46, v47
	ds_bpermute_b32 v222, v169, v140
	s_waitcnt lgkmcnt(0)
	s_addk_i32 s83, 0x80
	s_add_i32 s93, s93, 2
	s_add_i32 s87, s87, 64
	s_waitcnt lgkmcnt(0)
	v_max3_f32 v140, v233, v140, v222
	v_sub_f32_e32 v32, v32, v140
	v_exp_f32_e32 v223, v32
	v_sub_f32_e32 v32, v33, v140
	v_exp_f32_e32 v33, v32
	v_sub_f32_e32 v32, v34, v140
	v_exp_f32_e32 v224, v32
	v_sub_f32_e32 v32, v35, v140
	v_exp_f32_e32 v35, v32
	v_sub_f32_e32 v32, v36, v140
	v_exp_f32_e32 v36, v32
	v_sub_f32_e32 v32, v37, v140
	v_add_f32_e32 v34, 0, v223
	v_exp_f32_e32 v37, v32
	v_sub_f32_e32 v32, v38, v140
	v_add_f32_e32 v34, v33, v34
	v_exp_f32_e32 v38, v32
	v_sub_f32_e32 v32, v39, v140
	v_add_f32_e32 v34, v224, v34
	v_exp_f32_e32 v39, v32
	v_sub_f32_e32 v32, v40, v140
	v_add_f32_e32 v34, v35, v34
	v_exp_f32_e32 v225, v32
	v_sub_f32_e32 v32, v41, v140
	v_add_f32_e32 v34, v36, v34
	v_exp_f32_e32 v226, v32
	v_sub_f32_e32 v32, v42, v140
	v_add_f32_e32 v34, v37, v34
	v_exp_f32_e32 v42, v32
	v_sub_f32_e32 v32, v43, v140
	v_add_f32_e32 v34, v38, v34
	v_exp_f32_e32 v43, v32
	v_sub_f32_e32 v32, v44, v140
	v_add_f32_e32 v34, v39, v34
	v_exp_f32_e32 v44, v32
	v_sub_f32_e32 v32, v45, v140
	v_add_f32_e32 v34, v225, v34
	v_exp_f32_e32 v45, v32
	v_sub_f32_e32 v32, v46, v140
	v_add_f32_e32 v34, v226, v34
	v_sub_f32_e32 v222, v233, v140
	v_exp_f32_e32 v46, v32
	v_sub_f32_e32 v32, v47, v140
	v_add_f32_e32 v34, v42, v34
	v_exp_f32_e32 v47, v32
	v_exp_f32_e32 v32, v222
	v_add_f32_e32 v34, v43, v34
	v_add_f32_e32 v34, v44, v34
	v_add_f32_e32 v34, v45, v34
	v_add_f32_e32 v34, v46, v34
	v_pk_mul_f32 v[14:15], v[14:15], v[32:33] op_sel_hi:[1,0]
	v_pk_mul_f32 v[12:13], v[12:13], v[32:33] op_sel_hi:[1,0]
	v_pk_mul_f32 v[10:11], v[10:11], v[32:33] op_sel_hi:[1,0]
	v_pk_mul_f32 v[8:9], v[8:9], v[32:33] op_sel_hi:[1,0]
	v_pk_mul_f32 v[6:7], v[6:7], v[32:33] op_sel_hi:[1,0]
	v_pk_mul_f32 v[4:5], v[4:5], v[32:33] op_sel_hi:[1,0]
	v_pk_mul_f32 v[2:3], v[2:3], v[32:33] op_sel_hi:[1,0]
	v_pk_mul_f32 v[0:1], v[0:1], v[32:33] op_sel_hi:[1,0]
	v_add_f32_e32 v232, v47, v34
	v_cvt_pk_bf16_f32 v34, v223, v33
	v_cvt_pk_bf16_f32 v35, v224, v35
	v_cvt_pk_bf16_f32 v36, v36, v37
	v_cvt_pk_bf16_f32 v37, v38, v39
	ds_read_b64_tr_b16 v[38:39], v229
	ds_read_b64_tr_b16 v[40:41], v229 offset:1152
	s_waitcnt lgkmcnt(2)
	v_pk_mul_f32 v[30:31], v[30:31], v[32:33] op_sel_hi:[1,0]
	s_waitcnt lgkmcnt(0)
	v_pk_mul_f32 v[28:29], v[28:29], v[32:33] op_sel_hi:[1,0]
	v_pk_mul_f32 v[26:27], v[26:27], v[32:33] op_sel_hi:[1,0]
	v_pk_mul_f32 v[24:25], v[24:25], v[32:33] op_sel_hi:[1,0]
	v_pk_mul_f32 v[22:23], v[22:23], v[32:33] op_sel_hi:[1,0]
	v_pk_mul_f32 v[20:21], v[20:21], v[32:33] op_sel_hi:[1,0]
	v_pk_mul_f32 v[18:19], v[18:19], v[32:33] op_sel_hi:[1,0]
	v_pk_mul_f32 v[16:17], v[16:17], v[32:33] op_sel_hi:[1,0]
	v_fmac_f32_e32 v232, v234, v32
	s_cmp_lt_u32 s33, s84
	v_mfma_f32_32x32x16_bf16 v[16:31], v[38:41], v[34:37], v[16:31]
	ds_read_b64_tr_b16 v[38:39], v229 offset:64
	ds_read_b64_tr_b16 v[40:41], v229 offset:1216
	s_waitcnt lgkmcnt(2)
	s_waitcnt lgkmcnt(0)
	s_nop 1
	v_mfma_f32_32x32x16_bf16 v[0:15], v[38:41], v[34:37], v[0:15]
	v_cvt_pk_bf16_f32 v35, v42, v43
	v_cvt_pk_bf16_f32 v36, v44, v45
	ds_read_b64_tr_b16 v[38:39], v229 offset:2304
	ds_read_b64_tr_b16 v[40:41], v229 offset:3456
	s_waitcnt lgkmcnt(2)
	v_cvt_pk_bf16_f32 v34, v225, v226
	s_waitcnt lgkmcnt(0)
	v_cvt_pk_bf16_f32 v37, v46, v47
	s_nop 1
	v_mfma_f32_32x32x16_bf16 v[16:31], v[38:41], v[34:37], v[16:31]
	ds_read_b64_tr_b16 v[38:39], v229 offset:2368
	ds_read_b64_tr_b16 v[40:41], v229 offset:3520
	s_waitcnt lgkmcnt(2)
	s_waitcnt lgkmcnt(0)
	s_nop 1
	v_mfma_f32_32x32x16_bf16 v[0:15], v[38:41], v[34:37], v[0:15]
	s_cbranch_scc0 .LBB0_595

.LBB0_619:
	s_nop 3
	v_max_f32_e32 v222, v33, v33
	v_max_f32_e32 v223, v32, v32
	v_max_f32_e32 v222, v223, v222
	v_max3_f32 v222, v222, v34, v35
	v_max3_f32 v222, v222, v36, v37
	v_max3_f32 v222, v222, v38, v39
	v_max3_f32 v222, v222, v40, v41
	v_max3_f32 v222, v222, v42, v43
	v_max3_f32 v222, v222, v44, v45
	v_max3_f32 v222, v222, v46, v47
	ds_bpermute_b32 v223, v169, v222
	s_waitcnt lgkmcnt(0)
	s_add_i32 s0, s93, 17
	s_cmp_ge_u32 s0, s84
	s_waitcnt lgkmcnt(0)
	v_max3_f32 v233, v140, v222, v223
	v_sub_f32_e32 v32, v32, v233
	v_exp_f32_e32 v234, v32
	v_sub_f32_e32 v32, v33, v233
	v_exp_f32_e32 v235, v32
	v_sub_f32_e32 v32, v34, v233
	v_exp_f32_e32 v236, v32
	v_sub_f32_e32 v32, v35, v233
	v_exp_f32_e32 v237, v32
	v_sub_f32_e32 v32, v36, v233
	v_exp_f32_e32 v238, v32
	v_sub_f32_e32 v32, v37, v233
	v_exp_f32_e32 v239, v32
	v_sub_f32_e32 v32, v38, v233
	v_exp_f32_e32 v240, v32
	v_sub_f32_e32 v32, v39, v233
	v_exp_f32_e32 v241, v32
	v_sub_f32_e32 v32, v40, v233
	v_exp_f32_e32 v242, v32
	v_sub_f32_e32 v32, v41, v233
	v_exp_f32_e32 v243, v32
	v_sub_f32_e32 v32, v42, v233
	v_exp_f32_e32 v244, v32
	v_sub_f32_e32 v32, v43, v233
	ds_read_b64_tr_b16 v[36:37], v229
	ds_read_b64_tr_b16 v[38:39], v229 offset:1152
	v_sub_f32_e32 v140, v140, v233
	v_exp_f32_e32 v245, v32
	v_sub_f32_e32 v32, v44, v233
	v_exp_f32_e32 v140, v140
	s_waitcnt lgkmcnt(2)
	s_waitcnt lgkmcnt(0)
	v_exp_f32_e32 v246, v32
	v_sub_f32_e32 v32, v45, v233
	v_exp_f32_e32 v247, v32
	v_sub_f32_e32 v32, v46, v233
	v_exp_f32_e32 v248, v32
	v_sub_f32_e32 v32, v47, v233
	v_exp_f32_e32 v249, v32
	v_cvt_pk_bf16_f32 v32, v234, v235
	v_cvt_pk_bf16_f32 v33, v236, v237
	v_cvt_pk_bf16_f32 v34, v238, v239
	v_cvt_pk_bf16_f32 v35, v240, v241
	v_pk_mul_f32 v[30:31], v[30:31], v[140:141] op_sel_hi:[1,0]
	v_pk_mul_f32 v[28:29], v[28:29], v[140:141] op_sel_hi:[1,0]
	v_pk_mul_f32 v[26:27], v[26:27], v[140:141] op_sel_hi:[1,0]
	v_pk_mul_f32 v[24:25], v[24:25], v[140:141] op_sel_hi:[1,0]
	v_pk_mul_f32 v[22:23], v[22:23], v[140:141] op_sel_hi:[1,0]
	v_pk_mul_f32 v[20:21], v[20:21], v[140:141] op_sel_hi:[1,0]
	v_pk_mul_f32 v[18:19], v[18:19], v[140:141] op_sel_hi:[1,0]
	v_pk_mul_f32 v[16:17], v[16:17], v[140:141] op_sel_hi:[1,0]
	v_pk_mul_f32 v[14:15], v[14:15], v[140:141] op_sel_hi:[1,0]
	v_pk_mul_f32 v[12:13], v[12:13], v[140:141] op_sel_hi:[1,0]
	v_mfma_f32_32x32x16_bf16 v[16:31], v[36:39], v[32:35], v[16:31]
	ds_read_b64_tr_b16 v[36:37], v229 offset:64
	ds_read_b64_tr_b16 v[38:39], v229 offset:1216
	s_waitcnt lgkmcnt(2)
	v_pk_mul_f32 v[10:11], v[10:11], v[140:141] op_sel_hi:[1,0]
	s_waitcnt lgkmcnt(0)
	v_pk_mul_f32 v[8:9], v[8:9], v[140:141] op_sel_hi:[1,0]
	v_pk_mul_f32 v[6:7], v[6:7], v[140:141] op_sel_hi:[1,0]
	v_pk_mul_f32 v[4:5], v[4:5], v[140:141] op_sel_hi:[1,0]
	v_pk_mul_f32 v[2:3], v[2:3], v[140:141] op_sel_hi:[1,0]
	v_pk_mul_f32 v[0:1], v[0:1], v[140:141] op_sel_hi:[1,0]
	s_nop 1
	v_mfma_f32_32x32x16_bf16 v[0:15], v[36:39], v[32:35], v[0:15]
	ds_read_b64_tr_b16 v[36:37], v229 offset:2304
	ds_read_b64_tr_b16 v[38:39], v229 offset:3456
	s_waitcnt lgkmcnt(2)
	v_cvt_pk_bf16_f32 v32, v242, v243
	s_waitcnt lgkmcnt(0)
	v_cvt_pk_bf16_f32 v33, v244, v245
	v_cvt_pk_bf16_f32 v34, v246, v247
	v_cvt_pk_bf16_f32 v35, v248, v249
	s_nop 1
	v_mfma_f32_32x32x16_bf16 v[16:31], v[36:39], v[32:35], v[16:31]
	ds_read_b64_tr_b16 v[36:37], v229 offset:2368
	ds_read_b64_tr_b16 v[38:39], v229 offset:3520
	s_waitcnt lgkmcnt(2)
	s_waitcnt lgkmcnt(0)
	s_waitcnt vmcnt(3)
	ds_write_b128 v184, v[112:115]
	s_waitcnt vmcnt(0)
	ds_write_b128 v184, v[124:127] offset:16
	ds_write_b128 v184, v[120:123] offset:32
	ds_write_b128 v184, v[116:119] offset:48
	v_mfma_f32_32x32x16_bf16 v[0:15], v[36:39], v[32:35], v[0:15]
	v_mfma_f32_32x32x16_bf16 v[32:47], v[96:99], v[48:51], 0
	v_mfma_f32_32x32x16_bf16 v[32:47], v[100:103], v[52:55], v[32:47]
	v_mfma_f32_32x32x16_bf16 v[32:47], v[104:107], v[56:59], v[32:47]
	v_mfma_f32_32x32x16_bf16 v[32:47], v[108:111], v[60:63], v[32:47]
	s_cbranch_scc1 .LBB0_623
	s_cmp_lt_u32 s81, 13
	s_cselect_b64 vcc, -1, 0
	s_and_b64 vcc, s[76:77], vcc
	s_and_b64 vcc, exec, vcc
	s_mov_b32 s1, s87
	s_cbranch_vccnz .LBB0_622
	s_add_i32 s1, s93, 1
	s_and_b64 vcc, s[76:77], exec
	s_cselect_b32 s0, s1, s0
	s_lshl_b32 s0, s0, 5
	s_add_i32 s1, s0, s86

; __device__ __forceinline__ float bflo(unsigned u) { return __uint_as_float(u << 16); }
; __device__ __forceinline__ float bfhi(unsigned u) { return __uint_as_float(u & 0xffff0000u); }
; __device__ __forceinline__ int opaque_v(int x) { asm volatile("" : "+v"(x)); return x; }
; __device__ __forceinline__ void lru_pass1_item(const float* __restrict__ LA, const float* __restrict__ LU, float* __restrict__ AGG, int item) {
;     const int g = item * 512 + opaque_v(threadIdx.x), ch = (g & 255) * 4, dir = (g >> 8) & 1, bc = g >> 9, c = bc % NCHUNK, b = bc / NCHUNK;
;     const int row0 = chunk_row0(b, c);
;     const unsigned* ap = (const unsigned*)LA + ((size_t)dir * MROWS + row0) * 1024 + ch; (void)LU;
;     f32x4 A = {1.f, 1.f, 1.f, 1.f}, H = {0.f, 0.f, 0.f, 0.f};
; #pragma unroll 8
;     for (int t = 0; t < 64; ++t) { const int tt = dir ? 63 - t : t; const u32x4 w = *(const u32x4*)(ap + (size_t)tt * 1024);
;         const f32x4 a = {1.f - bflo(w.x), 1.f - bflo(w.y), 1.f - bflo(w.z), 1.f - bflo(w.w)}, u = {bfhi(w.x), bfhi(w.y), bfhi(w.z), bfhi(w.w)}; A *= a; H = a * H + u; }
;     float* o = AGG + (((size_t)(dir * NB + b) * NCHUNK + c) * 1024 + ch) * 2;
;     *(f32x4*)o = (f32x4){A[0], H[0], A[1], H[1]}; *(f32x4*)(o + 4) = (f32x4){A[2], H[2], A[3], H[3]};
; __global__ void __launch_bounds__(512, 2) mk_fwd(Args args) {
;     ...
;             for (int it = bid; it < (NB * NCHUNK * 2 * 256) / 512; it += G) lru_pass1_item(LA, LU, AGG, it);
.LBB0_625:
	v_readlane_b32 s68, v255, 33
	s_cmpk_eq_i32 s89, 0x100
	s_cbranch_scc0 .Lp1_norot
	s_addk_i32 s91, 0x80
	s_and_b32 s91, s91, 0xff
.Lp1_norot:
	v_readlane_b32 s74, v255, 22
	v_readlane_b32 s10, v255, 35
	s_cmpk_gt_i32 s91, 0x10f
	v_readlane_b32 s69, v255, 34
	v_readlane_b32 s75, v255, 23
	v_readlane_b32 s11, v255, 36
	s_movk_i32 s8, 0x44
	s_cbranch_scc1 .LBB0_634
	s_add_u32 s0, s90, 0x45e66000
	v_readlane_b32 s3, v255, 37
	s_addc_u32 s1, s3, 0
	s_add_u32 s2, s90, 0x56e66000
	s_addc_u32 s3, s3, 0
.LBB0_627:
	s_nop 0
	v_mov_b32_e32 v3, v252
	s_mov_b32 s4, 0x78787879
	v_lshl_add_u32 v0, s91, 9, v3
	v_ashrrev_i32_e32 v0, 9, v0
	v_mul_hi_i32 v1, v0, s4
	v_lshrrev_b32_e32 v2, 31, v1
	v_ashrrev_i32_e32 v1, 5, v1
	v_add_u32_e32 v1, v1, v2
	v_mul_lo_u32 v2, v1, s8
	v_sub_u32_e32 v0, v0, v2
	v_cmp_lt_i32_e32 vcc, 3, v0
	v_lshlrev_b32_e32 v4, 6, v0
	s_and_saveexec_b64 s[4:5], vcc
	s_xor_b64 s[4:5], exec, s[4:5]
	v_lshlrev_b32_e32 v2, 12, v1
	s_movk_i32 s6, 0xff00
	v_add3_u32 v2, v2, v4, s6
	s_andn2_saveexec_b64 s[4:5], s[4:5]
	v_lshlrev_b32_e32 v2, 8, v1
	s_movk_i32 s6, 0x4000
	v_add3_u32 v2, v2, v4, s6
	s_or_b64 exec, exec, s[4:5]
	v_bfe_u32 v5, v3, 8, 1
	v_lshlrev_b32_e32 v4, 2, v3
	v_mul_u32_u24_e32 v194, 0x4400, v5
	v_ashrrev_i32_e32 v3, 31, v2
	v_lshl_add_u64 v[2:3], v[2:3], 0, v[194:195]
	v_and_b32_e32 v4, 0x3fc, v4
	v_lshlrev_b64 v[2:3], 12, v[2:3]
	v_lshl_add_u64 v[2:3], s[0:1], 0, v[2:3]
	v_lshlrev_b32_e32 v194, 2, v4
	v_mov_b32_e32 v6, 0
	v_mov_b32_e32 v12, 1.0
	v_lshl_add_u64 v[8:9], v[2:3], 0, v[194:195]
	s_mov_b32 s4, 0
	v_cmp_eq_u32_e32 vcc, 0, v5
	s_mov_b32 s5, 56
	v_mov_b32_e32 v13, v12
	v_mov_b32_e32 v10, v12
	v_mov_b32_e32 v11, v12
	v_mov_b32_e32 v7, v6
	v_mov_b32_e32 v2, v6
	v_mov_b32_e32 v3, v6
	v_mov_b32_e32 v14, 0x1000
	v_mov_b32_e32 v15, 0xfffff000
	v_mov_b32_e32 v16, 0x3f000
	v_mov_b32_e32 v29, 0
	v_cndmask_b32_e32 v26, v15, v14, vcc
	v_cndmask_b32_e64 v27, -1, 0, vcc
	v_cndmask_b32_e64 v28, v16, 0, vcc
	v_lshl_add_u64 v[8:9], v[28:29], 0, v[8:9]
	global_load_dwordx4 v[96:99], v[8:9], off
	v_lshl_add_u64 v[8:9], v[26:27], 0, v[8:9]
	global_load_dwordx4 v[100:103], v[8:9], off
	v_lshl_add_u64 v[8:9], v[26:27], 0, v[8:9]
	global_load_dwordx4 v[104:107], v[8:9], off
	v_lshl_add_u64 v[8:9], v[26:27], 0, v[8:9]
	global_load_dwordx4 v[108:111], v[8:9], off
	v_lshl_add_u64 v[8:9], v[26:27], 0, v[8:9]
	global_load_dwordx4 v[112:115], v[8:9], off
	v_lshl_add_u64 v[8:9], v[26:27], 0, v[8:9]
	global_load_dwordx4 v[116:119], v[8:9], off
	v_lshl_add_u64 v[8:9], v[26:27], 0, v[8:9]
	global_load_dwordx4 v[120:123], v[8:9], off
	v_lshl_add_u64 v[8:9], v[26:27], 0, v[8:9]
	global_load_dwordx4 v[124:127], v[8:9], off
	v_lshl_add_u64 v[8:9], v[26:27], 0, v[8:9]
	global_load_dwordx4 v[128:131], v[8:9], off
	v_lshl_add_u64 v[8:9], v[26:27], 0, v[8:9]
	global_load_dwordx4 v[132:135], v[8:9], off
	v_lshl_add_u64 v[8:9], v[26:27], 0, v[8:9]
	global_load_dwordx4 v[136:139], v[8:9], off
	v_lshl_add_u64 v[8:9], v[26:27], 0, v[8:9]
	global_load_dwordx4 v[140:143], v[8:9], off
	v_lshl_add_u64 v[8:9], v[26:27], 0, v[8:9]
	global_load_dwordx4 v[144:147], v[8:9], off
	v_lshl_add_u64 v[8:9], v[26:27], 0, v[8:9]
	global_load_dwordx4 v[148:151], v[8:9], off
	v_lshl_add_u64 v[8:9], v[26:27], 0, v[8:9]
	global_load_dwordx4 v[152:155], v[8:9], off
	v_lshl_add_u64 v[8:9], v[26:27], 0, v[8:9]
	global_load_dwordx4 v[156:159], v[8:9], off
	v_lshl_add_u64 v[8:9], v[26:27], 0, v[8:9]
	s_waitcnt vmcnt(15)
	v_lshlrev_b32_e32 v14, 16, v96
	v_lshlrev_b32_e32 v15, 16, v97
	v_lshlrev_b32_e32 v16, 16, v98
	v_lshlrev_b32_e32 v17, 16, v99
	v_sub_f32_e32 v14, 1.0, v14
	v_sub_f32_e32 v15, 1.0, v15
	v_sub_f32_e32 v16, 1.0, v16
	v_sub_f32_e32 v17, 1.0, v17
	v_and_b32_e32 v18, 0xffff0000, v96
	v_and_b32_e32 v19, 0xffff0000, v97
	v_and_b32_e32 v20, 0xffff0000, v98
	v_and_b32_e32 v21, 0xffff0000, v99
	v_pk_mul_f32 v[12:13], v[12:13], v[14:15]
	v_pk_mul_f32 v[10:11], v[10:11], v[16:17]
	v_pk_fma_f32 v[6:7], v[6:7], v[14:15], v[18:19]
	v_pk_fma_f32 v[2:3], v[2:3], v[16:17], v[20:21]
	global_load_dwordx4 v[96:99], v[8:9], off
	v_lshl_add_u64 v[8:9], v[26:27], 0, v[8:9]
	s_waitcnt vmcnt(15)
	v_lshlrev_b32_e32 v14, 16, v100
	v_lshlrev_b32_e32 v15, 16, v101
	v_lshlrev_b32_e32 v16, 16, v102
	v_lshlrev_b32_e32 v17, 16, v103
	v_sub_f32_e32 v14, 1.0, v14
	v_sub_f32_e32 v15, 1.0, v15
	v_sub_f32_e32 v16, 1.0, v16
	v_sub_f32_e32 v17, 1.0, v17
	v_and_b32_e32 v18, 0xffff0000, v100
	v_and_b32_e32 v19, 0xffff0000, v101
	v_and_b32_e32 v20, 0xffff0000, v102
	v_and_b32_e32 v21, 0xffff0000, v103
	v_pk_mul_f32 v[12:13], v[12:13], v[14:15]
	v_pk_mul_f32 v[10:11], v[10:11], v[16:17]
	v_pk_fma_f32 v[6:7], v[6:7], v[14:15], v[18:19]
	v_pk_fma_f32 v[2:3], v[2:3], v[16:17], v[20:21]
	global_load_dwordx4 v[100:103], v[8:9], off
	v_lshl_add_u64 v[8:9], v[26:27], 0, v[8:9]
	s_waitcnt vmcnt(15)
	v_lshlrev_b32_e32 v14, 16, v104
	v_lshlrev_b32_e32 v15, 16, v105
	v_lshlrev_b32_e32 v16, 16, v106
	v_lshlrev_b32_e32 v17, 16, v107
	v_sub_f32_e32 v14, 1.0, v14
	v_sub_f32_e32 v15, 1.0, v15
	v_sub_f32_e32 v16, 1.0, v16
	v_sub_f32_e32 v17, 1.0, v17
	v_and_b32_e32 v18, 0xffff0000, v104
	v_and_b32_e32 v19, 0xffff0000, v105
	v_and_b32_e32 v20, 0xffff0000, v106
	v_and_b32_e32 v21, 0xffff0000, v107
	v_pk_mul_f32 v[12:13], v[12:13], v[14:15]
	v_pk_mul_f32 v[10:11], v[10:11], v[16:17]
	v_pk_fma_f32 v[6:7], v[6:7], v[14:15], v[18:19]
	v_pk_fma_f32 v[2:3], v[2:3], v[16:17], v[20:21]
	global_load_dwordx4 v[104:107], v[8:9], off
	v_lshl_add_u64 v[8:9], v[26:27], 0, v[8:9]
	s_waitcnt vmcnt(15)
; __device__ __forceinline__ float bflo(unsigned u) { return __uint_as_float(u << 16); }
; __device__ __forceinline__ float bfhi(unsigned u) { return __uint_as_float(u & 0xffff0000u); }
; __device__ __forceinline__ void lru_pass1_item(const float* __restrict__ LA, const float* __restrict__ LU, float* __restrict__ AGG, int item) {
;     ...
;     for (int t = 0; t < 64; ++t) { const int tt = dir ? 63 - t : t; const u32x4 w = *(const u32x4*)(ap + (size_t)tt * 1024);
;         const f32x4 a = {1.f - bflo(w.x), 1.f - bflo(w.y), 1.f - bflo(w.z), 1.f - bflo(w.w)}, u = {bfhi(w.x), bfhi(w.y), bfhi(w.z), bfhi(w.w)}; A *= a; H = a * H + u; }
	v_lshlrev_b32_e32 v14, 16, v108
	v_lshlrev_b32_e32 v15, 16, v109
	v_lshlrev_b32_e32 v16, 16, v110
	v_lshlrev_b32_e32 v17, 16, v111
	v_sub_f32_e32 v14, 1.0, v14
	v_sub_f32_e32 v15, 1.0, v15
	v_sub_f32_e32 v16, 1.0, v16
	v_sub_f32_e32 v17, 1.0, v17
	v_and_b32_e32 v18, 0xffff0000, v108
	v_and_b32_e32 v19, 0xffff0000, v109
	v_and_b32_e32 v20, 0xffff0000, v110
	v_and_b32_e32 v21, 0xffff0000, v111
	v_pk_mul_f32 v[12:13], v[12:13], v[14:15]
	v_pk_mul_f32 v[10:11], v[10:11], v[16:17]
	v_pk_fma_f32 v[6:7], v[6:7], v[14:15], v[18:19]
	v_pk_fma_f32 v[2:3], v[2:3], v[16:17], v[20:21]
	global_load_dwordx4 v[108:111], v[8:9], off
	v_lshl_add_u64 v[8:9], v[26:27], 0, v[8:9]
	s_waitcnt vmcnt(15)
	v_lshlrev_b32_e32 v14, 16, v112
	v_lshlrev_b32_e32 v15, 16, v113
	v_lshlrev_b32_e32 v16, 16, v114
	v_lshlrev_b32_e32 v17, 16, v115
	v_sub_f32_e32 v14, 1.0, v14
	v_sub_f32_e32 v15, 1.0, v15
	v_sub_f32_e32 v16, 1.0, v16
	v_sub_f32_e32 v17, 1.0, v17
	v_and_b32_e32 v18, 0xffff0000, v112
	v_and_b32_e32 v19, 0xffff0000, v113
	v_and_b32_e32 v20, 0xffff0000, v114
	v_and_b32_e32 v21, 0xffff0000, v115
	v_pk_mul_f32 v[12:13], v[12:13], v[14:15]
	v_pk_mul_f32 v[10:11], v[10:11], v[16:17]
	v_pk_fma_f32 v[6:7], v[6:7], v[14:15], v[18:19]
	v_pk_fma_f32 v[2:3], v[2:3], v[16:17], v[20:21]
	global_load_dwordx4 v[112:115], v[8:9], off
	v_lshl_add_u64 v[8:9], v[26:27], 0, v[8:9]
	s_waitcnt vmcnt(15)
	v_lshlrev_b32_e32 v14, 16, v116
	v_lshlrev_b32_e32 v15, 16, v117
	v_lshlrev_b32_e32 v16, 16, v118
	v_lshlrev_b32_e32 v17, 16, v119
	v_sub_f32_e32 v14, 1.0, v14
	v_sub_f32_e32 v15, 1.0, v15
	v_sub_f32_e32 v16, 1.0, v16
	v_sub_f32_e32 v17, 1.0, v17
	v_and_b32_e32 v18, 0xffff0000, v116
	v_and_b32_e32 v19, 0xffff0000, v117
	v_and_b32_e32 v20, 0xffff0000, v118
	v_and_b32_e32 v21, 0xffff0000, v119
	v_pk_mul_f32 v[12:13], v[12:13], v[14:15]
	v_pk_mul_f32 v[10:11], v[10:11], v[16:17]
	v_pk_fma_f32 v[6:7], v[6:7], v[14:15], v[18:19]
	v_pk_fma_f32 v[2:3], v[2:3], v[16:17], v[20:21]
	global_load_dwordx4 v[116:119], v[8:9], off
	v_lshl_add_u64 v[8:9], v[26:27], 0, v[8:9]
	s_waitcnt vmcnt(15)
	v_lshlrev_b32_e32 v14, 16, v120
	v_lshlrev_b32_e32 v15, 16, v121
	v_lshlrev_b32_e32 v16, 16, v122
	v_lshlrev_b32_e32 v17, 16, v123
	v_sub_f32_e32 v14, 1.0, v14
	v_sub_f32_e32 v15, 1.0, v15
	v_sub_f32_e32 v16, 1.0, v16
	v_sub_f32_e32 v17, 1.0, v17
	v_and_b32_e32 v18, 0xffff0000, v120
	v_and_b32_e32 v19, 0xffff0000, v121
	v_and_b32_e32 v20, 0xffff0000, v122
	v_and_b32_e32 v21, 0xffff0000, v123
	v_pk_mul_f32 v[12:13], v[12:13], v[14:15]
	v_pk_mul_f32 v[10:11], v[10:11], v[16:17]
	v_pk_fma_f32 v[6:7], v[6:7], v[14:15], v[18:19]
	v_pk_fma_f32 v[2:3], v[2:3], v[16:17], v[20:21]
	global_load_dwordx4 v[120:123], v[8:9], off
	v_lshl_add_u64 v[8:9], v[26:27], 0, v[8:9]
	s_waitcnt vmcnt(15)
	v_lshlrev_b32_e32 v14, 16, v124
	v_lshlrev_b32_e32 v15, 16, v125
	v_lshlrev_b32_e32 v16, 16, v126
	v_lshlrev_b32_e32 v17, 16, v127
	v_sub_f32_e32 v14, 1.0, v14
	v_sub_f32_e32 v15, 1.0, v15
	v_sub_f32_e32 v16, 1.0, v16
	v_sub_f32_e32 v17, 1.0, v17
	v_and_b32_e32 v18, 0xffff0000, v124
	v_and_b32_e32 v19, 0xffff0000, v125
	v_and_b32_e32 v20, 0xffff0000, v126
	v_and_b32_e32 v21, 0xffff0000, v127
	v_pk_mul_f32 v[12:13], v[12:13], v[14:15]
	v_pk_mul_f32 v[10:11], v[10:11], v[16:17]
	v_pk_fma_f32 v[6:7], v[6:7], v[14:15], v[18:19]
	v_pk_fma_f32 v[2:3], v[2:3], v[16:17], v[20:21]
	global_load_dwordx4 v[124:127], v[8:9], off
	v_lshl_add_u64 v[8:9], v[26:27], 0, v[8:9]
	s_waitcnt vmcnt(15)
	v_lshlrev_b32_e32 v14, 16, v128
	v_lshlrev_b32_e32 v15, 16, v129
	v_lshlrev_b32_e32 v16, 16, v130
	v_lshlrev_b32_e32 v17, 16, v131
	v_sub_f32_e32 v14, 1.0, v14
	v_sub_f32_e32 v15, 1.0, v15
	v_sub_f32_e32 v16, 1.0, v16
	v_sub_f32_e32 v17, 1.0, v17
	v_and_b32_e32 v18, 0xffff0000, v128
	v_and_b32_e32 v19, 0xffff0000, v129
	v_and_b32_e32 v20, 0xffff0000, v130
	v_and_b32_e32 v21, 0xffff0000, v131
	v_pk_mul_f32 v[12:13], v[12:13], v[14:15]
	v_pk_mul_f32 v[10:11], v[10:11], v[16:17]
	v_pk_fma_f32 v[6:7], v[6:7], v[14:15], v[18:19]
	v_pk_fma_f32 v[2:3], v[2:3], v[16:17], v[20:21]
	global_load_dwordx4 v[128:131], v[8:9], off
	v_lshl_add_u64 v[8:9], v[26:27], 0, v[8:9]
	s_waitcnt vmcnt(15)
	v_lshlrev_b32_e32 v14, 16, v132
	v_lshlrev_b32_e32 v15, 16, v133
	v_lshlrev_b32_e32 v16, 16, v134
	v_lshlrev_b32_e32 v17, 16, v135
	v_sub_f32_e32 v14, 1.0, v14
	v_sub_f32_e32 v15, 1.0, v15
	v_sub_f32_e32 v16, 1.0, v16
	v_sub_f32_e32 v17, 1.0, v17
	v_and_b32_e32 v18, 0xffff0000, v132
	v_and_b32_e32 v19, 0xffff0000, v133
	v_and_b32_e32 v20, 0xffff0000, v134
	v_and_b32_e32 v21, 0xffff0000, v135
	v_pk_mul_f32 v[12:13], v[12:13], v[14:15]
	v_pk_mul_f32 v[10:11], v[10:11], v[16:17]
	v_pk_fma_f32 v[6:7], v[6:7], v[14:15], v[18:19]
	v_pk_fma_f32 v[2:3], v[2:3], v[16:17], v[20:21]
	global_load_dwordx4 v[132:135], v[8:9], off
	v_lshl_add_u64 v[8:9], v[26:27], 0, v[8:9]
	s_waitcnt vmcnt(15)
	v_lshlrev_b32_e32 v14, 16, v136
	v_lshlrev_b32_e32 v15, 16, v137
	v_lshlrev_b32_e32 v16, 16, v138
	v_lshlrev_b32_e32 v17, 16, v139
	v_sub_f32_e32 v14, 1.0, v14
	v_sub_f32_e32 v15, 1.0, v15
	v_sub_f32_e32 v16, 1.0, v16
	v_sub_f32_e32 v17, 1.0, v17
	v_and_b32_e32 v18, 0xffff0000, v136
	v_and_b32_e32 v19, 0xffff0000, v137
	v_and_b32_e32 v20, 0xffff0000, v138
	v_and_b32_e32 v21, 0xffff0000, v139
	v_pk_mul_f32 v[12:13], v[12:13], v[14:15]
	v_pk_mul_f32 v[10:11], v[10:11], v[16:17]
	v_pk_fma_f32 v[6:7], v[6:7], v[14:15], v[18:19]
	v_pk_fma_f32 v[2:3], v[2:3], v[16:17], v[20:21]
	global_load_dwordx4 v[136:139], v[8:9], off
	v_lshl_add_u64 v[8:9], v[26:27], 0, v[8:9]
	s_waitcnt vmcnt(15)
; __device__ __forceinline__ float bflo(unsigned u) { return __uint_as_float(u << 16); }
; __device__ __forceinline__ float bfhi(unsigned u) { return __uint_as_float(u & 0xffff0000u); }
; __device__ __forceinline__ void lru_pass1_item(const float* __restrict__ LA, const float* __restrict__ LU, float* __restrict__ AGG, int item) {
;     ...
;     for (int t = 0; t < 64; ++t) { const int tt = dir ? 63 - t : t; const u32x4 w = *(const u32x4*)(ap + (size_t)tt * 1024);
;         const f32x4 a = {1.f - bflo(w.x), 1.f - bflo(w.y), 1.f - bflo(w.z), 1.f - bflo(w.w)}, u = {bfhi(w.x), bfhi(w.y), bfhi(w.z), bfhi(w.w)}; A *= a; H = a * H + u; }
	v_lshlrev_b32_e32 v14, 16, v140
	v_lshlrev_b32_e32 v15, 16, v141
	v_lshlrev_b32_e32 v16, 16, v142
	v_lshlrev_b32_e32 v17, 16, v143
	v_sub_f32_e32 v14, 1.0, v14
	v_sub_f32_e32 v15, 1.0, v15
	v_sub_f32_e32 v16, 1.0, v16
	v_sub_f32_e32 v17, 1.0, v17
	v_and_b32_e32 v18, 0xffff0000, v140
	v_and_b32_e32 v19, 0xffff0000, v141
	v_and_b32_e32 v20, 0xffff0000, v142
	v_and_b32_e32 v21, 0xffff0000, v143
	v_pk_mul_f32 v[12:13], v[12:13], v[14:15]
	v_pk_mul_f32 v[10:11], v[10:11], v[16:17]
	v_pk_fma_f32 v[6:7], v[6:7], v[14:15], v[18:19]
	v_pk_fma_f32 v[2:3], v[2:3], v[16:17], v[20:21]
	global_load_dwordx4 v[140:143], v[8:9], off
	v_lshl_add_u64 v[8:9], v[26:27], 0, v[8:9]
	s_waitcnt vmcnt(15)
	v_lshlrev_b32_e32 v14, 16, v144
	v_lshlrev_b32_e32 v15, 16, v145
	v_lshlrev_b32_e32 v16, 16, v146
	v_lshlrev_b32_e32 v17, 16, v147
	v_sub_f32_e32 v14, 1.0, v14
	v_sub_f32_e32 v15, 1.0, v15
	v_sub_f32_e32 v16, 1.0, v16
	v_sub_f32_e32 v17, 1.0, v17
	v_and_b32_e32 v18, 0xffff0000, v144
	v_and_b32_e32 v19, 0xffff0000, v145
	v_and_b32_e32 v20, 0xffff0000, v146
	v_and_b32_e32 v21, 0xffff0000, v147
	v_pk_mul_f32 v[12:13], v[12:13], v[14:15]
	v_pk_mul_f32 v[10:11], v[10:11], v[16:17]
	v_pk_fma_f32 v[6:7], v[6:7], v[14:15], v[18:19]
	v_pk_fma_f32 v[2:3], v[2:3], v[16:17], v[20:21]
	global_load_dwordx4 v[144:147], v[8:9], off
	v_lshl_add_u64 v[8:9], v[26:27], 0, v[8:9]
	s_waitcnt vmcnt(15)
	v_lshlrev_b32_e32 v14, 16, v148
	v_lshlrev_b32_e32 v15, 16, v149
	v_lshlrev_b32_e32 v16, 16, v150
	v_lshlrev_b32_e32 v17, 16, v151
	v_sub_f32_e32 v14, 1.0, v14
	v_sub_f32_e32 v15, 1.0, v15
	v_sub_f32_e32 v16, 1.0, v16
	v_sub_f32_e32 v17, 1.0, v17
	v_and_b32_e32 v18, 0xffff0000, v148
	v_and_b32_e32 v19, 0xffff0000, v149
	v_and_b32_e32 v20, 0xffff0000, v150
	v_and_b32_e32 v21, 0xffff0000, v151
	v_pk_mul_f32 v[12:13], v[12:13], v[14:15]
	v_pk_mul_f32 v[10:11], v[10:11], v[16:17]
	v_pk_fma_f32 v[6:7], v[6:7], v[14:15], v[18:19]
	v_pk_fma_f32 v[2:3], v[2:3], v[16:17], v[20:21]
	global_load_dwordx4 v[148:151], v[8:9], off
	v_lshl_add_u64 v[8:9], v[26:27], 0, v[8:9]
	s_waitcnt vmcnt(15)
	v_lshlrev_b32_e32 v14, 16, v152
	v_lshlrev_b32_e32 v15, 16, v153
	v_lshlrev_b32_e32 v16, 16, v154
	v_lshlrev_b32_e32 v17, 16, v155
	v_sub_f32_e32 v14, 1.0, v14
	v_sub_f32_e32 v15, 1.0, v15
	v_sub_f32_e32 v16, 1.0, v16
	v_sub_f32_e32 v17, 1.0, v17
	v_and_b32_e32 v18, 0xffff0000, v152
	v_and_b32_e32 v19, 0xffff0000, v153
	v_and_b32_e32 v20, 0xffff0000, v154
	v_and_b32_e32 v21, 0xffff0000, v155
	v_pk_mul_f32 v[12:13], v[12:13], v[14:15]
	v_pk_mul_f32 v[10:11], v[10:11], v[16:17]
	v_pk_fma_f32 v[6:7], v[6:7], v[14:15], v[18:19]
	v_pk_fma_f32 v[2:3], v[2:3], v[16:17], v[20:21]
	global_load_dwordx4 v[152:155], v[8:9], off
	v_lshl_add_u64 v[8:9], v[26:27], 0, v[8:9]
	s_waitcnt vmcnt(15)
	v_lshlrev_b32_e32 v14, 16, v156
	v_lshlrev_b32_e32 v15, 16, v157
	v_lshlrev_b32_e32 v16, 16, v158
	v_lshlrev_b32_e32 v17, 16, v159
	v_sub_f32_e32 v14, 1.0, v14
	v_sub_f32_e32 v15, 1.0, v15
	v_sub_f32_e32 v16, 1.0, v16
	v_sub_f32_e32 v17, 1.0, v17
	v_and_b32_e32 v18, 0xffff0000, v156
	v_and_b32_e32 v19, 0xffff0000, v157
	v_and_b32_e32 v20, 0xffff0000, v158
	v_and_b32_e32 v21, 0xffff0000, v159
	v_pk_mul_f32 v[12:13], v[12:13], v[14:15]
	v_pk_mul_f32 v[10:11], v[10:11], v[16:17]
	v_pk_fma_f32 v[6:7], v[6:7], v[14:15], v[18:19]
	v_pk_fma_f32 v[2:3], v[2:3], v[16:17], v[20:21]
	global_load_dwordx4 v[156:159], v[8:9], off
	v_lshl_add_u64 v[8:9], v[26:27], 0, v[8:9]
	s_waitcnt vmcnt(15)
	v_lshlrev_b32_e32 v14, 16, v96
	v_lshlrev_b32_e32 v15, 16, v97
	v_lshlrev_b32_e32 v16, 16, v98
	v_lshlrev_b32_e32 v17, 16, v99
	v_sub_f32_e32 v14, 1.0, v14
	v_sub_f32_e32 v15, 1.0, v15
	v_sub_f32_e32 v16, 1.0, v16
	v_sub_f32_e32 v17, 1.0, v17
	v_and_b32_e32 v18, 0xffff0000, v96
	v_and_b32_e32 v19, 0xffff0000, v97
	v_and_b32_e32 v20, 0xffff0000, v98
	v_and_b32_e32 v21, 0xffff0000, v99
	v_pk_mul_f32 v[12:13], v[12:13], v[14:15]
	v_pk_mul_f32 v[10:11], v[10:11], v[16:17]
	v_pk_fma_f32 v[6:7], v[6:7], v[14:15], v[18:19]
	v_pk_fma_f32 v[2:3], v[2:3], v[16:17], v[20:21]
	global_load_dwordx4 v[96:99], v[8:9], off
	v_lshl_add_u64 v[8:9], v[26:27], 0, v[8:9]
	s_waitcnt vmcnt(15)
	v_lshlrev_b32_e32 v14, 16, v100
	v_lshlrev_b32_e32 v15, 16, v101
	v_lshlrev_b32_e32 v16, 16, v102
	v_lshlrev_b32_e32 v17, 16, v103
	v_sub_f32_e32 v14, 1.0, v14
	v_sub_f32_e32 v15, 1.0, v15
	v_sub_f32_e32 v16, 1.0, v16
	v_sub_f32_e32 v17, 1.0, v17
	v_and_b32_e32 v18, 0xffff0000, v100
	v_and_b32_e32 v19, 0xffff0000, v101
	v_and_b32_e32 v20, 0xffff0000, v102
	v_and_b32_e32 v21, 0xffff0000, v103
	v_pk_mul_f32 v[12:13], v[12:13], v[14:15]
	v_pk_mul_f32 v[10:11], v[10:11], v[16:17]
	v_pk_fma_f32 v[6:7], v[6:7], v[14:15], v[18:19]
	v_pk_fma_f32 v[2:3], v[2:3], v[16:17], v[20:21]
	global_load_dwordx4 v[100:103], v[8:9], off
	v_lshl_add_u64 v[8:9], v[26:27], 0, v[8:9]
	s_waitcnt vmcnt(15)
	v_lshlrev_b32_e32 v14, 16, v104
	v_lshlrev_b32_e32 v15, 16, v105
	v_lshlrev_b32_e32 v16, 16, v106
	v_lshlrev_b32_e32 v17, 16, v107
	v_sub_f32_e32 v14, 1.0, v14
	v_sub_f32_e32 v15, 1.0, v15
	v_sub_f32_e32 v16, 1.0, v16
	v_sub_f32_e32 v17, 1.0, v17
	v_and_b32_e32 v18, 0xffff0000, v104
	v_and_b32_e32 v19, 0xffff0000, v105
	v_and_b32_e32 v20, 0xffff0000, v106
	v_and_b32_e32 v21, 0xffff0000, v107
	v_pk_mul_f32 v[12:13], v[12:13], v[14:15]
	v_pk_mul_f32 v[10:11], v[10:11], v[16:17]
	v_pk_fma_f32 v[6:7], v[6:7], v[14:15], v[18:19]
	v_pk_fma_f32 v[2:3], v[2:3], v[16:17], v[20:21]
	global_load_dwordx4 v[104:107], v[8:9], off
	v_lshl_add_u64 v[8:9], v[26:27], 0, v[8:9]
	s_waitcnt vmcnt(15)
; __device__ __forceinline__ float bflo(unsigned u) { return __uint_as_float(u << 16); }
; __device__ __forceinline__ float bfhi(unsigned u) { return __uint_as_float(u & 0xffff0000u); }
; __device__ __forceinline__ void lru_pass1_item(const float* __restrict__ LA, const float* __restrict__ LU, float* __restrict__ AGG, int item) {
;     ...
;     for (int t = 0; t < 64; ++t) { const int tt = dir ? 63 - t : t; const u32x4 w = *(const u32x4*)(ap + (size_t)tt * 1024);
;         const f32x4 a = {1.f - bflo(w.x), 1.f - bflo(w.y), 1.f - bflo(w.z), 1.f - bflo(w.w)}, u = {bfhi(w.x), bfhi(w.y), bfhi(w.z), bfhi(w.w)}; A *= a; H = a * H + u; }
	v_lshlrev_b32_e32 v14, 16, v108
	v_lshlrev_b32_e32 v15, 16, v109
	v_lshlrev_b32_e32 v16, 16, v110
	v_lshlrev_b32_e32 v17, 16, v111
	v_sub_f32_e32 v14, 1.0, v14
	v_sub_f32_e32 v15, 1.0, v15
	v_sub_f32_e32 v16, 1.0, v16
	v_sub_f32_e32 v17, 1.0, v17
	v_and_b32_e32 v18, 0xffff0000, v108
	v_and_b32_e32 v19, 0xffff0000, v109
	v_and_b32_e32 v20, 0xffff0000, v110
	v_and_b32_e32 v21, 0xffff0000, v111
	v_pk_mul_f32 v[12:13], v[12:13], v[14:15]
	v_pk_mul_f32 v[10:11], v[10:11], v[16:17]
	v_pk_fma_f32 v[6:7], v[6:7], v[14:15], v[18:19]
	v_pk_fma_f32 v[2:3], v[2:3], v[16:17], v[20:21]
	global_load_dwordx4 v[108:111], v[8:9], off
	v_lshl_add_u64 v[8:9], v[26:27], 0, v[8:9]
	s_waitcnt vmcnt(15)
	v_lshlrev_b32_e32 v14, 16, v112
	v_lshlrev_b32_e32 v15, 16, v113
	v_lshlrev_b32_e32 v16, 16, v114
	v_lshlrev_b32_e32 v17, 16, v115
	v_sub_f32_e32 v14, 1.0, v14
	v_sub_f32_e32 v15, 1.0, v15
	v_sub_f32_e32 v16, 1.0, v16
	v_sub_f32_e32 v17, 1.0, v17
	v_and_b32_e32 v18, 0xffff0000, v112
	v_and_b32_e32 v19, 0xffff0000, v113
	v_and_b32_e32 v20, 0xffff0000, v114
	v_and_b32_e32 v21, 0xffff0000, v115
	v_pk_mul_f32 v[12:13], v[12:13], v[14:15]
	v_pk_mul_f32 v[10:11], v[10:11], v[16:17]
	v_pk_fma_f32 v[6:7], v[6:7], v[14:15], v[18:19]
	v_pk_fma_f32 v[2:3], v[2:3], v[16:17], v[20:21]
	global_load_dwordx4 v[112:115], v[8:9], off
	v_lshl_add_u64 v[8:9], v[26:27], 0, v[8:9]
	s_waitcnt vmcnt(15)
	v_lshlrev_b32_e32 v14, 16, v116
	v_lshlrev_b32_e32 v15, 16, v117
	v_lshlrev_b32_e32 v16, 16, v118
	v_lshlrev_b32_e32 v17, 16, v119
	v_sub_f32_e32 v14, 1.0, v14
	v_sub_f32_e32 v15, 1.0, v15
	v_sub_f32_e32 v16, 1.0, v16
	v_sub_f32_e32 v17, 1.0, v17
	v_and_b32_e32 v18, 0xffff0000, v116
	v_and_b32_e32 v19, 0xffff0000, v117
	v_and_b32_e32 v20, 0xffff0000, v118
	v_and_b32_e32 v21, 0xffff0000, v119
	v_pk_mul_f32 v[12:13], v[12:13], v[14:15]
	v_pk_mul_f32 v[10:11], v[10:11], v[16:17]
	v_pk_fma_f32 v[6:7], v[6:7], v[14:15], v[18:19]
	v_pk_fma_f32 v[2:3], v[2:3], v[16:17], v[20:21]
	global_load_dwordx4 v[116:119], v[8:9], off
	v_lshl_add_u64 v[8:9], v[26:27], 0, v[8:9]
	s_waitcnt vmcnt(15)
	v_lshlrev_b32_e32 v14, 16, v120
	v_lshlrev_b32_e32 v15, 16, v121
	v_lshlrev_b32_e32 v16, 16, v122
	v_lshlrev_b32_e32 v17, 16, v123
	v_sub_f32_e32 v14, 1.0, v14
	v_sub_f32_e32 v15, 1.0, v15
	v_sub_f32_e32 v16, 1.0, v16
	v_sub_f32_e32 v17, 1.0, v17
	v_and_b32_e32 v18, 0xffff0000, v120
	v_and_b32_e32 v19, 0xffff0000, v121
	v_and_b32_e32 v20, 0xffff0000, v122
	v_and_b32_e32 v21, 0xffff0000, v123
	v_pk_mul_f32 v[12:13], v[12:13], v[14:15]
	v_pk_mul_f32 v[10:11], v[10:11], v[16:17]
	v_pk_fma_f32 v[6:7], v[6:7], v[14:15], v[18:19]
	v_pk_fma_f32 v[2:3], v[2:3], v[16:17], v[20:21]
	global_load_dwordx4 v[120:123], v[8:9], off
	v_lshl_add_u64 v[8:9], v[26:27], 0, v[8:9]
	s_waitcnt vmcnt(15)
	v_lshlrev_b32_e32 v14, 16, v124
	v_lshlrev_b32_e32 v15, 16, v125
	v_lshlrev_b32_e32 v16, 16, v126
	v_lshlrev_b32_e32 v17, 16, v127
	v_sub_f32_e32 v14, 1.0, v14
	v_sub_f32_e32 v15, 1.0, v15
	v_sub_f32_e32 v16, 1.0, v16
	v_sub_f32_e32 v17, 1.0, v17
	v_and_b32_e32 v18, 0xffff0000, v124
	v_and_b32_e32 v19, 0xffff0000, v125
	v_and_b32_e32 v20, 0xffff0000, v126
	v_and_b32_e32 v21, 0xffff0000, v127
	v_pk_mul_f32 v[12:13], v[12:13], v[14:15]
	v_pk_mul_f32 v[10:11], v[10:11], v[16:17]
	v_pk_fma_f32 v[6:7], v[6:7], v[14:15], v[18:19]
	v_pk_fma_f32 v[2:3], v[2:3], v[16:17], v[20:21]
	global_load_dwordx4 v[124:127], v[8:9], off
	v_lshl_add_u64 v[8:9], v[26:27], 0, v[8:9]
	s_waitcnt vmcnt(15)
	v_lshlrev_b32_e32 v14, 16, v128
	v_lshlrev_b32_e32 v15, 16, v129
	v_lshlrev_b32_e32 v16, 16, v130
	v_lshlrev_b32_e32 v17, 16, v131
	v_sub_f32_e32 v14, 1.0, v14
	v_sub_f32_e32 v15, 1.0, v15
	v_sub_f32_e32 v16, 1.0, v16
	v_sub_f32_e32 v17, 1.0, v17
	v_and_b32_e32 v18, 0xffff0000, v128
	v_and_b32_e32 v19, 0xffff0000, v129
	v_and_b32_e32 v20, 0xffff0000, v130
	v_and_b32_e32 v21, 0xffff0000, v131
	v_pk_mul_f32 v[12:13], v[12:13], v[14:15]
	v_pk_mul_f32 v[10:11], v[10:11], v[16:17]
	v_pk_fma_f32 v[6:7], v[6:7], v[14:15], v[18:19]
	v_pk_fma_f32 v[2:3], v[2:3], v[16:17], v[20:21]
	global_load_dwordx4 v[128:131], v[8:9], off
	v_lshl_add_u64 v[8:9], v[26:27], 0, v[8:9]
	s_waitcnt vmcnt(15)
	v_lshlrev_b32_e32 v14, 16, v132
	v_lshlrev_b32_e32 v15, 16, v133
	v_lshlrev_b32_e32 v16, 16, v134
	v_lshlrev_b32_e32 v17, 16, v135
	v_sub_f32_e32 v14, 1.0, v14
	v_sub_f32_e32 v15, 1.0, v15
	v_sub_f32_e32 v16, 1.0, v16
	v_sub_f32_e32 v17, 1.0, v17
	v_and_b32_e32 v18, 0xffff0000, v132
	v_and_b32_e32 v19, 0xffff0000, v133
	v_and_b32_e32 v20, 0xffff0000, v134
	v_and_b32_e32 v21, 0xffff0000, v135
	v_pk_mul_f32 v[12:13], v[12:13], v[14:15]
	v_pk_mul_f32 v[10:11], v[10:11], v[16:17]
	v_pk_fma_f32 v[6:7], v[6:7], v[14:15], v[18:19]
	v_pk_fma_f32 v[2:3], v[2:3], v[16:17], v[20:21]
	global_load_dwordx4 v[132:135], v[8:9], off
	v_lshl_add_u64 v[8:9], v[26:27], 0, v[8:9]
	s_waitcnt vmcnt(15)
	v_lshlrev_b32_e32 v14, 16, v136
	v_lshlrev_b32_e32 v15, 16, v137
	v_lshlrev_b32_e32 v16, 16, v138
	v_lshlrev_b32_e32 v17, 16, v139
	v_sub_f32_e32 v14, 1.0, v14
	v_sub_f32_e32 v15, 1.0, v15
	v_sub_f32_e32 v16, 1.0, v16
	v_sub_f32_e32 v17, 1.0, v17
	v_and_b32_e32 v18, 0xffff0000, v136
	v_and_b32_e32 v19, 0xffff0000, v137
	v_and_b32_e32 v20, 0xffff0000, v138
	v_and_b32_e32 v21, 0xffff0000, v139
	v_pk_mul_f32 v[12:13], v[12:13], v[14:15]
	v_pk_mul_f32 v[10:11], v[10:11], v[16:17]
	v_pk_fma_f32 v[6:7], v[6:7], v[14:15], v[18:19]
	v_pk_fma_f32 v[2:3], v[2:3], v[16:17], v[20:21]
	global_load_dwordx4 v[136:139], v[8:9], off
	v_lshl_add_u64 v[8:9], v[26:27], 0, v[8:9]
	s_waitcnt vmcnt(15)
; __device__ __forceinline__ float bflo(unsigned u) { return __uint_as_float(u << 16); }
; __device__ __forceinline__ float bfhi(unsigned u) { return __uint_as_float(u & 0xffff0000u); }
; __device__ __forceinline__ void lru_pass1_item(const float* __restrict__ LA, const float* __restrict__ LU, float* __restrict__ AGG, int item) {
;     ...
;     for (int t = 0; t < 64; ++t) { const int tt = dir ? 63 - t : t; const u32x4 w = *(const u32x4*)(ap + (size_t)tt * 1024);
;         const f32x4 a = {1.f - bflo(w.x), 1.f - bflo(w.y), 1.f - bflo(w.z), 1.f - bflo(w.w)}, u = {bfhi(w.x), bfhi(w.y), bfhi(w.z), bfhi(w.w)}; A *= a; H = a * H + u; }
	v_lshlrev_b32_e32 v14, 16, v140
	v_lshlrev_b32_e32 v15, 16, v141
	v_lshlrev_b32_e32 v16, 16, v142
	v_lshlrev_b32_e32 v17, 16, v143
	v_sub_f32_e32 v14, 1.0, v14
	v_sub_f32_e32 v15, 1.0, v15
	v_sub_f32_e32 v16, 1.0, v16
	v_sub_f32_e32 v17, 1.0, v17
	v_and_b32_e32 v18, 0xffff0000, v140
	v_and_b32_e32 v19, 0xffff0000, v141
	v_and_b32_e32 v20, 0xffff0000, v142
	v_and_b32_e32 v21, 0xffff0000, v143
	v_pk_mul_f32 v[12:13], v[12:13], v[14:15]
	v_pk_mul_f32 v[10:11], v[10:11], v[16:17]
	v_pk_fma_f32 v[6:7], v[6:7], v[14:15], v[18:19]
	v_pk_fma_f32 v[2:3], v[2:3], v[16:17], v[20:21]
	global_load_dwordx4 v[140:143], v[8:9], off
	v_lshl_add_u64 v[8:9], v[26:27], 0, v[8:9]
	s_waitcnt vmcnt(15)
	v_lshlrev_b32_e32 v14, 16, v144
	v_lshlrev_b32_e32 v15, 16, v145
	v_lshlrev_b32_e32 v16, 16, v146
	v_lshlrev_b32_e32 v17, 16, v147
	v_sub_f32_e32 v14, 1.0, v14
	v_sub_f32_e32 v15, 1.0, v15
	v_sub_f32_e32 v16, 1.0, v16
	v_sub_f32_e32 v17, 1.0, v17
	v_and_b32_e32 v18, 0xffff0000, v144
	v_and_b32_e32 v19, 0xffff0000, v145
	v_and_b32_e32 v20, 0xffff0000, v146
	v_and_b32_e32 v21, 0xffff0000, v147
	v_pk_mul_f32 v[12:13], v[12:13], v[14:15]
	v_pk_mul_f32 v[10:11], v[10:11], v[16:17]
	v_pk_fma_f32 v[6:7], v[6:7], v[14:15], v[18:19]
	v_pk_fma_f32 v[2:3], v[2:3], v[16:17], v[20:21]
	global_load_dwordx4 v[144:147], v[8:9], off
	v_lshl_add_u64 v[8:9], v[26:27], 0, v[8:9]
	s_waitcnt vmcnt(15)
	v_lshlrev_b32_e32 v14, 16, v148
	v_lshlrev_b32_e32 v15, 16, v149
	v_lshlrev_b32_e32 v16, 16, v150
	v_lshlrev_b32_e32 v17, 16, v151
	v_sub_f32_e32 v14, 1.0, v14
	v_sub_f32_e32 v15, 1.0, v15
	v_sub_f32_e32 v16, 1.0, v16
	v_sub_f32_e32 v17, 1.0, v17
	v_and_b32_e32 v18, 0xffff0000, v148
	v_and_b32_e32 v19, 0xffff0000, v149
	v_and_b32_e32 v20, 0xffff0000, v150
	v_and_b32_e32 v21, 0xffff0000, v151
	v_pk_mul_f32 v[12:13], v[12:13], v[14:15]
	v_pk_mul_f32 v[10:11], v[10:11], v[16:17]
	v_pk_fma_f32 v[6:7], v[6:7], v[14:15], v[18:19]
	v_pk_fma_f32 v[2:3], v[2:3], v[16:17], v[20:21]
	global_load_dwordx4 v[148:151], v[8:9], off
	v_lshl_add_u64 v[8:9], v[26:27], 0, v[8:9]
	s_waitcnt vmcnt(15)
	v_lshlrev_b32_e32 v14, 16, v152
	v_lshlrev_b32_e32 v15, 16, v153
	v_lshlrev_b32_e32 v16, 16, v154
	v_lshlrev_b32_e32 v17, 16, v155
	v_sub_f32_e32 v14, 1.0, v14
	v_sub_f32_e32 v15, 1.0, v15
	v_sub_f32_e32 v16, 1.0, v16
	v_sub_f32_e32 v17, 1.0, v17
	v_and_b32_e32 v18, 0xffff0000, v152
	v_and_b32_e32 v19, 0xffff0000, v153
	v_and_b32_e32 v20, 0xffff0000, v154
	v_and_b32_e32 v21, 0xffff0000, v155
	v_pk_mul_f32 v[12:13], v[12:13], v[14:15]
	v_pk_mul_f32 v[10:11], v[10:11], v[16:17]
	v_pk_fma_f32 v[6:7], v[6:7], v[14:15], v[18:19]
	v_pk_fma_f32 v[2:3], v[2:3], v[16:17], v[20:21]
	global_load_dwordx4 v[152:155], v[8:9], off
	v_lshl_add_u64 v[8:9], v[26:27], 0, v[8:9]
	s_waitcnt vmcnt(15)
	v_lshlrev_b32_e32 v14, 16, v156
	v_lshlrev_b32_e32 v15, 16, v157
	v_lshlrev_b32_e32 v16, 16, v158
	v_lshlrev_b32_e32 v17, 16, v159
	v_sub_f32_e32 v14, 1.0, v14
	v_sub_f32_e32 v15, 1.0, v15
	v_sub_f32_e32 v16, 1.0, v16
	v_sub_f32_e32 v17, 1.0, v17
	v_and_b32_e32 v18, 0xffff0000, v156
	v_and_b32_e32 v19, 0xffff0000, v157
	v_and_b32_e32 v20, 0xffff0000, v158
	v_and_b32_e32 v21, 0xffff0000, v159
	v_pk_mul_f32 v[12:13], v[12:13], v[14:15]
	v_pk_mul_f32 v[10:11], v[10:11], v[16:17]
	v_pk_fma_f32 v[6:7], v[6:7], v[14:15], v[18:19]
	v_pk_fma_f32 v[2:3], v[2:3], v[16:17], v[20:21]
	global_load_dwordx4 v[156:159], v[8:9], off
	v_lshl_add_u64 v[8:9], v[26:27], 0, v[8:9]
	s_waitcnt vmcnt(15)
	v_lshlrev_b32_e32 v14, 16, v96
	v_lshlrev_b32_e32 v15, 16, v97
	v_lshlrev_b32_e32 v16, 16, v98
	v_lshlrev_b32_e32 v17, 16, v99
	v_sub_f32_e32 v14, 1.0, v14
	v_sub_f32_e32 v15, 1.0, v15
	v_sub_f32_e32 v16, 1.0, v16
	v_sub_f32_e32 v17, 1.0, v17
	v_and_b32_e32 v18, 0xffff0000, v96
	v_and_b32_e32 v19, 0xffff0000, v97
	v_and_b32_e32 v20, 0xffff0000, v98
	v_and_b32_e32 v21, 0xffff0000, v99
	v_pk_mul_f32 v[12:13], v[12:13], v[14:15]
	v_pk_mul_f32 v[10:11], v[10:11], v[16:17]
	v_pk_fma_f32 v[6:7], v[6:7], v[14:15], v[18:19]
	v_pk_fma_f32 v[2:3], v[2:3], v[16:17], v[20:21]
	global_load_dwordx4 v[96:99], v[8:9], off
	v_lshl_add_u64 v[8:9], v[26:27], 0, v[8:9]
	s_waitcnt vmcnt(15)
	v_lshlrev_b32_e32 v14, 16, v100
	v_lshlrev_b32_e32 v15, 16, v101
	v_lshlrev_b32_e32 v16, 16, v102
	v_lshlrev_b32_e32 v17, 16, v103
	v_sub_f32_e32 v14, 1.0, v14
	v_sub_f32_e32 v15, 1.0, v15
	v_sub_f32_e32 v16, 1.0, v16
	v_sub_f32_e32 v17, 1.0, v17
	v_and_b32_e32 v18, 0xffff0000, v100
	v_and_b32_e32 v19, 0xffff0000, v101
	v_and_b32_e32 v20, 0xffff0000, v102
	v_and_b32_e32 v21, 0xffff0000, v103
	v_pk_mul_f32 v[12:13], v[12:13], v[14:15]
	v_pk_mul_f32 v[10:11], v[10:11], v[16:17]
	v_pk_fma_f32 v[6:7], v[6:7], v[14:15], v[18:19]
	v_pk_fma_f32 v[2:3], v[2:3], v[16:17], v[20:21]
	global_load_dwordx4 v[100:103], v[8:9], off
	v_lshl_add_u64 v[8:9], v[26:27], 0, v[8:9]
	s_waitcnt vmcnt(15)
	v_lshlrev_b32_e32 v14, 16, v104
	v_lshlrev_b32_e32 v15, 16, v105
	v_lshlrev_b32_e32 v16, 16, v106
	v_lshlrev_b32_e32 v17, 16, v107
	v_sub_f32_e32 v14, 1.0, v14
	v_sub_f32_e32 v15, 1.0, v15
	v_sub_f32_e32 v16, 1.0, v16
	v_sub_f32_e32 v17, 1.0, v17
	v_and_b32_e32 v18, 0xffff0000, v104
	v_and_b32_e32 v19, 0xffff0000, v105
	v_and_b32_e32 v20, 0xffff0000, v106
	v_and_b32_e32 v21, 0xffff0000, v107
	v_pk_mul_f32 v[12:13], v[12:13], v[14:15]
	v_pk_mul_f32 v[10:11], v[10:11], v[16:17]
	v_pk_fma_f32 v[6:7], v[6:7], v[14:15], v[18:19]
	v_pk_fma_f32 v[2:3], v[2:3], v[16:17], v[20:21]
	global_load_dwordx4 v[104:107], v[8:9], off
	v_lshl_add_u64 v[8:9], v[26:27], 0, v[8:9]
	s_waitcnt vmcnt(15)
; __device__ __forceinline__ float bflo(unsigned u) { return __uint_as_float(u << 16); }
; __device__ __forceinline__ float bfhi(unsigned u) { return __uint_as_float(u & 0xffff0000u); }
; __device__ __forceinline__ void lru_pass1_item(const float* __restrict__ LA, const float* __restrict__ LU, float* __restrict__ AGG, int item) {
;     ...
;     for (int t = 0; t < 64; ++t) { const int tt = dir ? 63 - t : t; const u32x4 w = *(const u32x4*)(ap + (size_t)tt * 1024);
;         const f32x4 a = {1.f - bflo(w.x), 1.f - bflo(w.y), 1.f - bflo(w.z), 1.f - bflo(w.w)}, u = {bfhi(w.x), bfhi(w.y), bfhi(w.z), bfhi(w.w)}; A *= a; H = a * H + u; }
	v_lshlrev_b32_e32 v14, 16, v108
	v_lshlrev_b32_e32 v15, 16, v109
	v_lshlrev_b32_e32 v16, 16, v110
	v_lshlrev_b32_e32 v17, 16, v111
	v_sub_f32_e32 v14, 1.0, v14
	v_sub_f32_e32 v15, 1.0, v15
	v_sub_f32_e32 v16, 1.0, v16
	v_sub_f32_e32 v17, 1.0, v17
	v_and_b32_e32 v18, 0xffff0000, v108
	v_and_b32_e32 v19, 0xffff0000, v109
	v_and_b32_e32 v20, 0xffff0000, v110
	v_and_b32_e32 v21, 0xffff0000, v111
	v_pk_mul_f32 v[12:13], v[12:13], v[14:15]
	v_pk_mul_f32 v[10:11], v[10:11], v[16:17]
	v_pk_fma_f32 v[6:7], v[6:7], v[14:15], v[18:19]
	v_pk_fma_f32 v[2:3], v[2:3], v[16:17], v[20:21]
	global_load_dwordx4 v[108:111], v[8:9], off
	v_lshl_add_u64 v[8:9], v[26:27], 0, v[8:9]
	s_waitcnt vmcnt(15)
	v_lshlrev_b32_e32 v14, 16, v112
	v_lshlrev_b32_e32 v15, 16, v113
	v_lshlrev_b32_e32 v16, 16, v114
	v_lshlrev_b32_e32 v17, 16, v115
	v_sub_f32_e32 v14, 1.0, v14
	v_sub_f32_e32 v15, 1.0, v15
	v_sub_f32_e32 v16, 1.0, v16
	v_sub_f32_e32 v17, 1.0, v17
	v_and_b32_e32 v18, 0xffff0000, v112
	v_and_b32_e32 v19, 0xffff0000, v113
	v_and_b32_e32 v20, 0xffff0000, v114
	v_and_b32_e32 v21, 0xffff0000, v115
	v_pk_mul_f32 v[12:13], v[12:13], v[14:15]
	v_pk_mul_f32 v[10:11], v[10:11], v[16:17]
	v_pk_fma_f32 v[6:7], v[6:7], v[14:15], v[18:19]
	v_pk_fma_f32 v[2:3], v[2:3], v[16:17], v[20:21]
	global_load_dwordx4 v[112:115], v[8:9], off
	v_lshl_add_u64 v[8:9], v[26:27], 0, v[8:9]
	s_waitcnt vmcnt(15)
	v_lshlrev_b32_e32 v14, 16, v116
	v_lshlrev_b32_e32 v15, 16, v117
	v_lshlrev_b32_e32 v16, 16, v118
	v_lshlrev_b32_e32 v17, 16, v119
	v_sub_f32_e32 v14, 1.0, v14
	v_sub_f32_e32 v15, 1.0, v15
	v_sub_f32_e32 v16, 1.0, v16
	v_sub_f32_e32 v17, 1.0, v17
	v_and_b32_e32 v18, 0xffff0000, v116
	v_and_b32_e32 v19, 0xffff0000, v117
	v_and_b32_e32 v20, 0xffff0000, v118
	v_and_b32_e32 v21, 0xffff0000, v119
	v_pk_mul_f32 v[12:13], v[12:13], v[14:15]
	v_pk_mul_f32 v[10:11], v[10:11], v[16:17]
	v_pk_fma_f32 v[6:7], v[6:7], v[14:15], v[18:19]
	v_pk_fma_f32 v[2:3], v[2:3], v[16:17], v[20:21]
	global_load_dwordx4 v[116:119], v[8:9], off
	v_lshl_add_u64 v[8:9], v[26:27], 0, v[8:9]
	s_waitcnt vmcnt(15)
	v_lshlrev_b32_e32 v14, 16, v120
	v_lshlrev_b32_e32 v15, 16, v121
	v_lshlrev_b32_e32 v16, 16, v122
	v_lshlrev_b32_e32 v17, 16, v123
	v_sub_f32_e32 v14, 1.0, v14
	v_sub_f32_e32 v15, 1.0, v15
	v_sub_f32_e32 v16, 1.0, v16
	v_sub_f32_e32 v17, 1.0, v17
	v_and_b32_e32 v18, 0xffff0000, v120
	v_and_b32_e32 v19, 0xffff0000, v121
	v_and_b32_e32 v20, 0xffff0000, v122
	v_and_b32_e32 v21, 0xffff0000, v123
	v_pk_mul_f32 v[12:13], v[12:13], v[14:15]
	v_pk_mul_f32 v[10:11], v[10:11], v[16:17]
	v_pk_fma_f32 v[6:7], v[6:7], v[14:15], v[18:19]
	v_pk_fma_f32 v[2:3], v[2:3], v[16:17], v[20:21]
	global_load_dwordx4 v[120:123], v[8:9], off
	v_lshl_add_u64 v[8:9], v[26:27], 0, v[8:9]
	s_waitcnt vmcnt(15)
	v_lshlrev_b32_e32 v14, 16, v124
	v_lshlrev_b32_e32 v15, 16, v125
	v_lshlrev_b32_e32 v16, 16, v126
	v_lshlrev_b32_e32 v17, 16, v127
	v_sub_f32_e32 v14, 1.0, v14
	v_sub_f32_e32 v15, 1.0, v15
	v_sub_f32_e32 v16, 1.0, v16
	v_sub_f32_e32 v17, 1.0, v17
	v_and_b32_e32 v18, 0xffff0000, v124
	v_and_b32_e32 v19, 0xffff0000, v125
	v_and_b32_e32 v20, 0xffff0000, v126
	v_and_b32_e32 v21, 0xffff0000, v127
	v_pk_mul_f32 v[12:13], v[12:13], v[14:15]
	v_pk_mul_f32 v[10:11], v[10:11], v[16:17]
	v_pk_fma_f32 v[6:7], v[6:7], v[14:15], v[18:19]
	v_pk_fma_f32 v[2:3], v[2:3], v[16:17], v[20:21]
	global_load_dwordx4 v[124:127], v[8:9], off
	v_lshl_add_u64 v[8:9], v[26:27], 0, v[8:9]
	s_waitcnt vmcnt(15)
	v_lshlrev_b32_e32 v14, 16, v128
	v_lshlrev_b32_e32 v15, 16, v129
	v_lshlrev_b32_e32 v16, 16, v130
	v_lshlrev_b32_e32 v17, 16, v131
	v_sub_f32_e32 v14, 1.0, v14
	v_sub_f32_e32 v15, 1.0, v15
	v_sub_f32_e32 v16, 1.0, v16
	v_sub_f32_e32 v17, 1.0, v17
	v_and_b32_e32 v18, 0xffff0000, v128
	v_and_b32_e32 v19, 0xffff0000, v129
	v_and_b32_e32 v20, 0xffff0000, v130
	v_and_b32_e32 v21, 0xffff0000, v131
	v_pk_mul_f32 v[12:13], v[12:13], v[14:15]
	v_pk_mul_f32 v[10:11], v[10:11], v[16:17]
	v_pk_fma_f32 v[6:7], v[6:7], v[14:15], v[18:19]
	v_pk_fma_f32 v[2:3], v[2:3], v[16:17], v[20:21]
	global_load_dwordx4 v[128:131], v[8:9], off
	v_lshl_add_u64 v[8:9], v[26:27], 0, v[8:9]
	s_waitcnt vmcnt(15)
	v_lshlrev_b32_e32 v14, 16, v132
	v_lshlrev_b32_e32 v15, 16, v133
	v_lshlrev_b32_e32 v16, 16, v134
	v_lshlrev_b32_e32 v17, 16, v135
	v_sub_f32_e32 v14, 1.0, v14
	v_sub_f32_e32 v15, 1.0, v15
	v_sub_f32_e32 v16, 1.0, v16
	v_sub_f32_e32 v17, 1.0, v17
	v_and_b32_e32 v18, 0xffff0000, v132
	v_and_b32_e32 v19, 0xffff0000, v133
	v_and_b32_e32 v20, 0xffff0000, v134
	v_and_b32_e32 v21, 0xffff0000, v135
	v_pk_mul_f32 v[12:13], v[12:13], v[14:15]
	v_pk_mul_f32 v[10:11], v[10:11], v[16:17]
	v_pk_fma_f32 v[6:7], v[6:7], v[14:15], v[18:19]
	v_pk_fma_f32 v[2:3], v[2:3], v[16:17], v[20:21]
	global_load_dwordx4 v[132:135], v[8:9], off
	v_lshl_add_u64 v[8:9], v[26:27], 0, v[8:9]
	s_waitcnt vmcnt(15)
	v_lshlrev_b32_e32 v14, 16, v136
	v_lshlrev_b32_e32 v15, 16, v137
	v_lshlrev_b32_e32 v16, 16, v138
	v_lshlrev_b32_e32 v17, 16, v139
	v_sub_f32_e32 v14, 1.0, v14
	v_sub_f32_e32 v15, 1.0, v15
	v_sub_f32_e32 v16, 1.0, v16
	v_sub_f32_e32 v17, 1.0, v17
	v_and_b32_e32 v18, 0xffff0000, v136
	v_and_b32_e32 v19, 0xffff0000, v137
	v_and_b32_e32 v20, 0xffff0000, v138
	v_and_b32_e32 v21, 0xffff0000, v139
	v_pk_mul_f32 v[12:13], v[12:13], v[14:15]
	v_pk_mul_f32 v[10:11], v[10:11], v[16:17]
	v_pk_fma_f32 v[6:7], v[6:7], v[14:15], v[18:19]
	v_pk_fma_f32 v[2:3], v[2:3], v[16:17], v[20:21]
	global_load_dwordx4 v[136:139], v[8:9], off
	v_lshl_add_u64 v[8:9], v[26:27], 0, v[8:9]
	s_waitcnt vmcnt(15)
; __device__ __forceinline__ float bflo(unsigned u) { return __uint_as_float(u << 16); }
; __device__ __forceinline__ float bfhi(unsigned u) { return __uint_as_float(u & 0xffff0000u); }
; __device__ __forceinline__ void lru_pass1_item(const float* __restrict__ LA, const float* __restrict__ LU, float* __restrict__ AGG, int item) {
;     ...
;     for (int t = 0; t < 64; ++t) { const int tt = dir ? 63 - t : t; const u32x4 w = *(const u32x4*)(ap + (size_t)tt * 1024);
;         const f32x4 a = {1.f - bflo(w.x), 1.f - bflo(w.y), 1.f - bflo(w.z), 1.f - bflo(w.w)}, u = {bfhi(w.x), bfhi(w.y), bfhi(w.z), bfhi(w.w)}; A *= a; H = a * H + u; }
	v_lshlrev_b32_e32 v14, 16, v140
	v_lshlrev_b32_e32 v15, 16, v141
	v_lshlrev_b32_e32 v16, 16, v142
	v_lshlrev_b32_e32 v17, 16, v143
	v_sub_f32_e32 v14, 1.0, v14
	v_sub_f32_e32 v15, 1.0, v15
	v_sub_f32_e32 v16, 1.0, v16
	v_sub_f32_e32 v17, 1.0, v17
	v_and_b32_e32 v18, 0xffff0000, v140
	v_and_b32_e32 v19, 0xffff0000, v141
	v_and_b32_e32 v20, 0xffff0000, v142
	v_and_b32_e32 v21, 0xffff0000, v143
	v_pk_mul_f32 v[12:13], v[12:13], v[14:15]
	v_pk_mul_f32 v[10:11], v[10:11], v[16:17]
	v_pk_fma_f32 v[6:7], v[6:7], v[14:15], v[18:19]
	v_pk_fma_f32 v[2:3], v[2:3], v[16:17], v[20:21]
	global_load_dwordx4 v[140:143], v[8:9], off
	v_lshl_add_u64 v[8:9], v[26:27], 0, v[8:9]
	s_waitcnt vmcnt(15)
	v_lshlrev_b32_e32 v14, 16, v144
	v_lshlrev_b32_e32 v15, 16, v145
	v_lshlrev_b32_e32 v16, 16, v146
	v_lshlrev_b32_e32 v17, 16, v147
	v_sub_f32_e32 v14, 1.0, v14
	v_sub_f32_e32 v15, 1.0, v15
	v_sub_f32_e32 v16, 1.0, v16
	v_sub_f32_e32 v17, 1.0, v17
	v_and_b32_e32 v18, 0xffff0000, v144
	v_and_b32_e32 v19, 0xffff0000, v145
	v_and_b32_e32 v20, 0xffff0000, v146
	v_and_b32_e32 v21, 0xffff0000, v147
	v_pk_mul_f32 v[12:13], v[12:13], v[14:15]
	v_pk_mul_f32 v[10:11], v[10:11], v[16:17]
	v_pk_fma_f32 v[6:7], v[6:7], v[14:15], v[18:19]
	v_pk_fma_f32 v[2:3], v[2:3], v[16:17], v[20:21]
	global_load_dwordx4 v[144:147], v[8:9], off
	v_lshl_add_u64 v[8:9], v[26:27], 0, v[8:9]
	s_waitcnt vmcnt(15)
	v_lshlrev_b32_e32 v14, 16, v148
	v_lshlrev_b32_e32 v15, 16, v149
	v_lshlrev_b32_e32 v16, 16, v150
	v_lshlrev_b32_e32 v17, 16, v151
	v_sub_f32_e32 v14, 1.0, v14
	v_sub_f32_e32 v15, 1.0, v15
	v_sub_f32_e32 v16, 1.0, v16
	v_sub_f32_e32 v17, 1.0, v17
	v_and_b32_e32 v18, 0xffff0000, v148
	v_and_b32_e32 v19, 0xffff0000, v149
	v_and_b32_e32 v20, 0xffff0000, v150
	v_and_b32_e32 v21, 0xffff0000, v151
	v_pk_mul_f32 v[12:13], v[12:13], v[14:15]
	v_pk_mul_f32 v[10:11], v[10:11], v[16:17]
	v_pk_fma_f32 v[6:7], v[6:7], v[14:15], v[18:19]
	v_pk_fma_f32 v[2:3], v[2:3], v[16:17], v[20:21]
	global_load_dwordx4 v[148:151], v[8:9], off
	v_lshl_add_u64 v[8:9], v[26:27], 0, v[8:9]
	s_waitcnt vmcnt(15)
	v_lshlrev_b32_e32 v14, 16, v152
	v_lshlrev_b32_e32 v15, 16, v153
	v_lshlrev_b32_e32 v16, 16, v154
	v_lshlrev_b32_e32 v17, 16, v155
	v_sub_f32_e32 v14, 1.0, v14
	v_sub_f32_e32 v15, 1.0, v15
	v_sub_f32_e32 v16, 1.0, v16
	v_sub_f32_e32 v17, 1.0, v17
	v_and_b32_e32 v18, 0xffff0000, v152
	v_and_b32_e32 v19, 0xffff0000, v153
	v_and_b32_e32 v20, 0xffff0000, v154
	v_and_b32_e32 v21, 0xffff0000, v155
	v_pk_mul_f32 v[12:13], v[12:13], v[14:15]
	v_pk_mul_f32 v[10:11], v[10:11], v[16:17]
	v_pk_fma_f32 v[6:7], v[6:7], v[14:15], v[18:19]
	v_pk_fma_f32 v[2:3], v[2:3], v[16:17], v[20:21]
	global_load_dwordx4 v[152:155], v[8:9], off
	v_lshl_add_u64 v[8:9], v[26:27], 0, v[8:9]
	s_waitcnt vmcnt(15)
	v_lshlrev_b32_e32 v14, 16, v156
	v_lshlrev_b32_e32 v15, 16, v157
	v_lshlrev_b32_e32 v16, 16, v158
	v_lshlrev_b32_e32 v17, 16, v159
	v_sub_f32_e32 v14, 1.0, v14
	v_sub_f32_e32 v15, 1.0, v15
	v_sub_f32_e32 v16, 1.0, v16
	v_sub_f32_e32 v17, 1.0, v17
	v_and_b32_e32 v18, 0xffff0000, v156
	v_and_b32_e32 v19, 0xffff0000, v157
	v_and_b32_e32 v20, 0xffff0000, v158
	v_and_b32_e32 v21, 0xffff0000, v159
	v_pk_mul_f32 v[12:13], v[12:13], v[14:15]
	v_pk_mul_f32 v[10:11], v[10:11], v[16:17]
	v_pk_fma_f32 v[6:7], v[6:7], v[14:15], v[18:19]
	v_pk_fma_f32 v[2:3], v[2:3], v[16:17], v[20:21]
	global_load_dwordx4 v[156:159], v[8:9], off
	s_waitcnt vmcnt(15)
	v_lshlrev_b32_e32 v14, 16, v96
	v_lshlrev_b32_e32 v15, 16, v97
	v_lshlrev_b32_e32 v16, 16, v98
	v_lshlrev_b32_e32 v17, 16, v99
	v_sub_f32_e32 v14, 1.0, v14
	v_sub_f32_e32 v15, 1.0, v15
	v_sub_f32_e32 v16, 1.0, v16
	v_sub_f32_e32 v17, 1.0, v17
	v_and_b32_e32 v18, 0xffff0000, v96
	v_and_b32_e32 v19, 0xffff0000, v97
	v_and_b32_e32 v20, 0xffff0000, v98
	v_and_b32_e32 v21, 0xffff0000, v99
	v_pk_mul_f32 v[12:13], v[12:13], v[14:15]
	v_pk_mul_f32 v[10:11], v[10:11], v[16:17]
	v_pk_fma_f32 v[6:7], v[6:7], v[14:15], v[18:19]
	v_pk_fma_f32 v[2:3], v[2:3], v[16:17], v[20:21]
	s_waitcnt vmcnt(14)
	v_lshlrev_b32_e32 v14, 16, v100
	v_lshlrev_b32_e32 v15, 16, v101
	v_lshlrev_b32_e32 v16, 16, v102
	v_lshlrev_b32_e32 v17, 16, v103
	v_sub_f32_e32 v14, 1.0, v14
	v_sub_f32_e32 v15, 1.0, v15
	v_sub_f32_e32 v16, 1.0, v16
	v_sub_f32_e32 v17, 1.0, v17
	v_and_b32_e32 v18, 0xffff0000, v100
	v_and_b32_e32 v19, 0xffff0000, v101
	v_and_b32_e32 v20, 0xffff0000, v102
	v_and_b32_e32 v21, 0xffff0000, v103
	v_pk_mul_f32 v[12:13], v[12:13], v[14:15]
	v_pk_mul_f32 v[10:11], v[10:11], v[16:17]
	v_pk_fma_f32 v[6:7], v[6:7], v[14:15], v[18:19]
	v_pk_fma_f32 v[2:3], v[2:3], v[16:17], v[20:21]
	s_waitcnt vmcnt(13)
	v_lshlrev_b32_e32 v14, 16, v104
	v_lshlrev_b32_e32 v15, 16, v105
	v_lshlrev_b32_e32 v16, 16, v106
	v_lshlrev_b32_e32 v17, 16, v107
	v_sub_f32_e32 v14, 1.0, v14
	v_sub_f32_e32 v15, 1.0, v15
	v_sub_f32_e32 v16, 1.0, v16
	v_sub_f32_e32 v17, 1.0, v17
	v_and_b32_e32 v18, 0xffff0000, v104
	v_and_b32_e32 v19, 0xffff0000, v105
	v_and_b32_e32 v20, 0xffff0000, v106
	v_and_b32_e32 v21, 0xffff0000, v107
	v_pk_mul_f32 v[12:13], v[12:13], v[14:15]
	v_pk_mul_f32 v[10:11], v[10:11], v[16:17]
	v_pk_fma_f32 v[6:7], v[6:7], v[14:15], v[18:19]
	v_pk_fma_f32 v[2:3], v[2:3], v[16:17], v[20:21]
	s_waitcnt vmcnt(12)
	v_lshlrev_b32_e32 v14, 16, v108
	v_lshlrev_b32_e32 v15, 16, v109
	v_lshlrev_b32_e32 v16, 16, v110
	v_lshlrev_b32_e32 v17, 16, v111
	v_sub_f32_e32 v14, 1.0, v14
	v_sub_f32_e32 v15, 1.0, v15
	v_sub_f32_e32 v16, 1.0, v16
	v_sub_f32_e32 v17, 1.0, v17
	v_and_b32_e32 v18, 0xffff0000, v108
	v_and_b32_e32 v19, 0xffff0000, v109
	v_and_b32_e32 v20, 0xffff0000, v110
	v_and_b32_e32 v21, 0xffff0000, v111
	v_pk_mul_f32 v[12:13], v[12:13], v[14:15]
	v_pk_mul_f32 v[10:11], v[10:11], v[16:17]
	v_pk_fma_f32 v[6:7], v[6:7], v[14:15], v[18:19]
	v_pk_fma_f32 v[2:3], v[2:3], v[16:17], v[20:21]
	s_waitcnt vmcnt(11)
; __device__ __forceinline__ float bflo(unsigned u) { return __uint_as_float(u << 16); }
; __device__ __forceinline__ float bfhi(unsigned u) { return __uint_as_float(u & 0xffff0000u); }
; __device__ __forceinline__ void lru_pass1_item(const float* __restrict__ LA, const float* __restrict__ LU, float* __restrict__ AGG, int item) {
;     ...
;     for (int t = 0; t < 64; ++t) { const int tt = dir ? 63 - t : t; const u32x4 w = *(const u32x4*)(ap + (size_t)tt * 1024);
;         const f32x4 a = {1.f - bflo(w.x), 1.f - bflo(w.y), 1.f - bflo(w.z), 1.f - bflo(w.w)}, u = {bfhi(w.x), bfhi(w.y), bfhi(w.z), bfhi(w.w)}; A *= a; H = a * H + u; }
	v_lshlrev_b32_e32 v14, 16, v112
	v_lshlrev_b32_e32 v15, 16, v113
	v_lshlrev_b32_e32 v16, 16, v114
	v_lshlrev_b32_e32 v17, 16, v115
	v_sub_f32_e32 v14, 1.0, v14
	v_sub_f32_e32 v15, 1.0, v15
	v_sub_f32_e32 v16, 1.0, v16
	v_sub_f32_e32 v17, 1.0, v17
	v_and_b32_e32 v18, 0xffff0000, v112
	v_and_b32_e32 v19, 0xffff0000, v113
	v_and_b32_e32 v20, 0xffff0000, v114
	v_and_b32_e32 v21, 0xffff0000, v115
	v_pk_mul_f32 v[12:13], v[12:13], v[14:15]
	v_pk_mul_f32 v[10:11], v[10:11], v[16:17]
	v_pk_fma_f32 v[6:7], v[6:7], v[14:15], v[18:19]
	v_pk_fma_f32 v[2:3], v[2:3], v[16:17], v[20:21]
	s_waitcnt vmcnt(10)
	v_lshlrev_b32_e32 v14, 16, v116
	v_lshlrev_b32_e32 v15, 16, v117
	v_lshlrev_b32_e32 v16, 16, v118
	v_lshlrev_b32_e32 v17, 16, v119
	v_sub_f32_e32 v14, 1.0, v14
	v_sub_f32_e32 v15, 1.0, v15
	v_sub_f32_e32 v16, 1.0, v16
	v_sub_f32_e32 v17, 1.0, v17
	v_and_b32_e32 v18, 0xffff0000, v116
	v_and_b32_e32 v19, 0xffff0000, v117
	v_and_b32_e32 v20, 0xffff0000, v118
	v_and_b32_e32 v21, 0xffff0000, v119
	v_pk_mul_f32 v[12:13], v[12:13], v[14:15]
	v_pk_mul_f32 v[10:11], v[10:11], v[16:17]
	v_pk_fma_f32 v[6:7], v[6:7], v[14:15], v[18:19]
	v_pk_fma_f32 v[2:3], v[2:3], v[16:17], v[20:21]
	s_waitcnt vmcnt(9)
	v_lshlrev_b32_e32 v14, 16, v120
	v_lshlrev_b32_e32 v15, 16, v121
	v_lshlrev_b32_e32 v16, 16, v122
	v_lshlrev_b32_e32 v17, 16, v123
	v_sub_f32_e32 v14, 1.0, v14
	v_sub_f32_e32 v15, 1.0, v15
	v_sub_f32_e32 v16, 1.0, v16
	v_sub_f32_e32 v17, 1.0, v17
	v_and_b32_e32 v18, 0xffff0000, v120
	v_and_b32_e32 v19, 0xffff0000, v121
	v_and_b32_e32 v20, 0xffff0000, v122
	v_and_b32_e32 v21, 0xffff0000, v123
	v_pk_mul_f32 v[12:13], v[12:13], v[14:15]
	v_pk_mul_f32 v[10:11], v[10:11], v[16:17]
	v_pk_fma_f32 v[6:7], v[6:7], v[14:15], v[18:19]
	v_pk_fma_f32 v[2:3], v[2:3], v[16:17], v[20:21]
	s_waitcnt vmcnt(8)
	v_lshlrev_b32_e32 v14, 16, v124
	v_lshlrev_b32_e32 v15, 16, v125
	v_lshlrev_b32_e32 v16, 16, v126
	v_lshlrev_b32_e32 v17, 16, v127
	v_sub_f32_e32 v14, 1.0, v14
	v_sub_f32_e32 v15, 1.0, v15
	v_sub_f32_e32 v16, 1.0, v16
	v_sub_f32_e32 v17, 1.0, v17
	v_and_b32_e32 v18, 0xffff0000, v124
	v_and_b32_e32 v19, 0xffff0000, v125
	v_and_b32_e32 v20, 0xffff0000, v126
	v_and_b32_e32 v21, 0xffff0000, v127
	v_pk_mul_f32 v[12:13], v[12:13], v[14:15]
	v_pk_mul_f32 v[10:11], v[10:11], v[16:17]
	v_pk_fma_f32 v[6:7], v[6:7], v[14:15], v[18:19]
	v_pk_fma_f32 v[2:3], v[2:3], v[16:17], v[20:21]
	s_waitcnt vmcnt(7)
	v_lshlrev_b32_e32 v14, 16, v128
	v_lshlrev_b32_e32 v15, 16, v129
	v_lshlrev_b32_e32 v16, 16, v130
	v_lshlrev_b32_e32 v17, 16, v131
	v_sub_f32_e32 v14, 1.0, v14
	v_sub_f32_e32 v15, 1.0, v15
	v_sub_f32_e32 v16, 1.0, v16
	v_sub_f32_e32 v17, 1.0, v17
	v_and_b32_e32 v18, 0xffff0000, v128
	v_and_b32_e32 v19, 0xffff0000, v129
	v_and_b32_e32 v20, 0xffff0000, v130
	v_and_b32_e32 v21, 0xffff0000, v131
	v_pk_mul_f32 v[12:13], v[12:13], v[14:15]
	v_pk_mul_f32 v[10:11], v[10:11], v[16:17]
	v_pk_fma_f32 v[6:7], v[6:7], v[14:15], v[18:19]
	v_pk_fma_f32 v[2:3], v[2:3], v[16:17], v[20:21]
	s_waitcnt vmcnt(6)
	v_lshlrev_b32_e32 v14, 16, v132
	v_lshlrev_b32_e32 v15, 16, v133
	v_lshlrev_b32_e32 v16, 16, v134
	v_lshlrev_b32_e32 v17, 16, v135
	v_sub_f32_e32 v14, 1.0, v14
	v_sub_f32_e32 v15, 1.0, v15
	v_sub_f32_e32 v16, 1.0, v16
	v_sub_f32_e32 v17, 1.0, v17
	v_and_b32_e32 v18, 0xffff0000, v132
	v_and_b32_e32 v19, 0xffff0000, v133
	v_and_b32_e32 v20, 0xffff0000, v134
	v_and_b32_e32 v21, 0xffff0000, v135
	v_pk_mul_f32 v[12:13], v[12:13], v[14:15]
	v_pk_mul_f32 v[10:11], v[10:11], v[16:17]
	v_pk_fma_f32 v[6:7], v[6:7], v[14:15], v[18:19]
	v_pk_fma_f32 v[2:3], v[2:3], v[16:17], v[20:21]
	s_waitcnt vmcnt(5)
; __device__ __forceinline__ float bflo(unsigned u) { return __uint_as_float(u << 16); }
; __device__ __forceinline__ float bfhi(unsigned u) { return __uint_as_float(u & 0xffff0000u); }
; __device__ __forceinline__ void lru_pass1_item(const float* __restrict__ LA, const float* __restrict__ LU, float* __restrict__ AGG, int item) {
;     ...
;     for (int t = 0; t < 64; ++t) { const int tt = dir ? 63 - t : t; const u32x4 w = *(const u32x4*)(ap + (size_t)tt * 1024);
;         const f32x4 a = {1.f - bflo(w.x), 1.f - bflo(w.y), 1.f - bflo(w.z), 1.f - bflo(w.w)}, u = {bfhi(w.x), bfhi(w.y), bfhi(w.z), bfhi(w.w)}; A *= a; H = a * H + u; }
;     float* o = AGG + (((size_t)(dir * NB + b) * NCHUNK + c) * 1024 + ch) * 2;
;     *(f32x4*)o = (f32x4){A[0], H[0], A[1], H[1]}; *(f32x4*)(o + 4) = (f32x4){A[2], H[2], A[3], H[3]};
; __global__ void __launch_bounds__(512, 2) mk_fwd(Args args) {
;     ...
;             for (int it = bid; it < (NB * NCHUNK * 2 * 256) / 512; it += G) lru_pass1_item(LA, LU, AGG, it);
	v_lshlrev_b32_e32 v14, 16, v136
	v_lshlrev_b32_e32 v15, 16, v137
	v_lshlrev_b32_e32 v16, 16, v138
	v_lshlrev_b32_e32 v17, 16, v139
	v_sub_f32_e32 v14, 1.0, v14
	v_sub_f32_e32 v15, 1.0, v15
	v_sub_f32_e32 v16, 1.0, v16
	v_sub_f32_e32 v17, 1.0, v17
	v_and_b32_e32 v18, 0xffff0000, v136
	v_and_b32_e32 v19, 0xffff0000, v137
	v_and_b32_e32 v20, 0xffff0000, v138
	v_and_b32_e32 v21, 0xffff0000, v139
	v_pk_mul_f32 v[12:13], v[12:13], v[14:15]
	v_pk_mul_f32 v[10:11], v[10:11], v[16:17]
	v_pk_fma_f32 v[6:7], v[6:7], v[14:15], v[18:19]
	v_pk_fma_f32 v[2:3], v[2:3], v[16:17], v[20:21]
	s_waitcnt vmcnt(4)
	v_lshlrev_b32_e32 v14, 16, v140
	v_lshlrev_b32_e32 v15, 16, v141
	v_lshlrev_b32_e32 v16, 16, v142
	v_lshlrev_b32_e32 v17, 16, v143
	v_sub_f32_e32 v14, 1.0, v14
	v_sub_f32_e32 v15, 1.0, v15
	v_sub_f32_e32 v16, 1.0, v16
	v_sub_f32_e32 v17, 1.0, v17
	v_and_b32_e32 v18, 0xffff0000, v140
	v_and_b32_e32 v19, 0xffff0000, v141
	v_and_b32_e32 v20, 0xffff0000, v142
	v_and_b32_e32 v21, 0xffff0000, v143
	v_pk_mul_f32 v[12:13], v[12:13], v[14:15]
	v_pk_mul_f32 v[10:11], v[10:11], v[16:17]
	v_pk_fma_f32 v[6:7], v[6:7], v[14:15], v[18:19]
	v_pk_fma_f32 v[2:3], v[2:3], v[16:17], v[20:21]
	s_waitcnt vmcnt(3)
	v_lshlrev_b32_e32 v14, 16, v144
	v_lshlrev_b32_e32 v15, 16, v145
	v_lshlrev_b32_e32 v16, 16, v146
	v_lshlrev_b32_e32 v17, 16, v147
	v_sub_f32_e32 v14, 1.0, v14
	v_sub_f32_e32 v15, 1.0, v15
	v_sub_f32_e32 v16, 1.0, v16
	v_sub_f32_e32 v17, 1.0, v17
	v_and_b32_e32 v18, 0xffff0000, v144
	v_and_b32_e32 v19, 0xffff0000, v145
	v_and_b32_e32 v20, 0xffff0000, v146
	v_and_b32_e32 v21, 0xffff0000, v147
	v_pk_mul_f32 v[12:13], v[12:13], v[14:15]
	v_pk_mul_f32 v[10:11], v[10:11], v[16:17]
	v_pk_fma_f32 v[6:7], v[6:7], v[14:15], v[18:19]
	v_pk_fma_f32 v[2:3], v[2:3], v[16:17], v[20:21]
	s_waitcnt vmcnt(2)
	v_lshlrev_b32_e32 v14, 16, v148
	v_lshlrev_b32_e32 v15, 16, v149
	v_lshlrev_b32_e32 v16, 16, v150
	v_lshlrev_b32_e32 v17, 16, v151
	v_sub_f32_e32 v14, 1.0, v14
	v_sub_f32_e32 v15, 1.0, v15
	v_sub_f32_e32 v16, 1.0, v16
	v_sub_f32_e32 v17, 1.0, v17
	v_and_b32_e32 v18, 0xffff0000, v148
	v_and_b32_e32 v19, 0xffff0000, v149
	v_and_b32_e32 v20, 0xffff0000, v150
	v_and_b32_e32 v21, 0xffff0000, v151
	v_pk_mul_f32 v[12:13], v[12:13], v[14:15]
	v_pk_mul_f32 v[10:11], v[10:11], v[16:17]
	v_pk_fma_f32 v[6:7], v[6:7], v[14:15], v[18:19]
	v_pk_fma_f32 v[2:3], v[2:3], v[16:17], v[20:21]
	s_waitcnt vmcnt(1)
	v_lshlrev_b32_e32 v14, 16, v152
	v_lshlrev_b32_e32 v15, 16, v153
	v_lshlrev_b32_e32 v16, 16, v154
	v_lshlrev_b32_e32 v17, 16, v155
	v_sub_f32_e32 v14, 1.0, v14
	v_sub_f32_e32 v15, 1.0, v15
	v_sub_f32_e32 v16, 1.0, v16
	v_sub_f32_e32 v17, 1.0, v17
	v_and_b32_e32 v18, 0xffff0000, v152
	v_and_b32_e32 v19, 0xffff0000, v153
	v_and_b32_e32 v20, 0xffff0000, v154
	v_and_b32_e32 v21, 0xffff0000, v155
	v_pk_mul_f32 v[12:13], v[12:13], v[14:15]
	v_pk_mul_f32 v[10:11], v[10:11], v[16:17]
	v_pk_fma_f32 v[6:7], v[6:7], v[14:15], v[18:19]
	v_pk_fma_f32 v[2:3], v[2:3], v[16:17], v[20:21]
	s_waitcnt vmcnt(0)
	v_lshlrev_b32_e32 v14, 16, v156
	v_lshlrev_b32_e32 v15, 16, v157
	v_lshlrev_b32_e32 v16, 16, v158
	v_lshlrev_b32_e32 v17, 16, v159
	v_sub_f32_e32 v14, 1.0, v14
	v_sub_f32_e32 v15, 1.0, v15
	v_sub_f32_e32 v16, 1.0, v16
	v_sub_f32_e32 v17, 1.0, v17
	v_and_b32_e32 v18, 0xffff0000, v156
	v_and_b32_e32 v19, 0xffff0000, v157
	v_and_b32_e32 v20, 0xffff0000, v158
	v_and_b32_e32 v21, 0xffff0000, v159
	v_pk_mul_f32 v[12:13], v[12:13], v[14:15]
	v_pk_mul_f32 v[10:11], v[10:11], v[16:17]
	v_pk_fma_f32 v[6:7], v[6:7], v[14:15], v[18:19]
	v_pk_fma_f32 v[2:3], v[2:3], v[16:17], v[20:21]
	v_lshl_add_u32 v1, v5, 2, v1
	v_mad_u64_u32 v[0:1], s[4:5], v1, s8, v[0:1]
	v_ashrrev_i32_e32 v1, 31, v0
	v_lshlrev_b64 v[0:1], 13, v[0:1]
	v_lshl_add_u64 v[0:1], s[2:3], 0, v[0:1]
	v_lshlrev_b32_e32 v194, 3, v4
	s_add_i32 s91, s91, s89
	v_lshl_add_u64 v[8:9], v[0:1], 0, v[194:195]
	v_mov_b32_e32 v4, v12
	v_mov_b32_e32 v5, v6
	v_mov_b32_e32 v6, v13
	v_mov_b32_e32 v0, v10
	v_mov_b32_e32 v1, v2
	v_mov_b32_e32 v2, v11
	s_cmpk_gt_i32 s91, 0x10f
	global_store_dwordx4 v[8:9], v[4:7], off
	global_store_dwordx4 v[8:9], v[0:3], off offset:16
	s_cbranch_scc0 .LBB0_627

; #define LAS __attribute__((address_space(3)))
; __device__ __forceinline__ float bflo(unsigned u) { return __uint_as_float(u << 16); }
; __device__ __forceinline__ float bfhi(unsigned u) { return __uint_as_float(u & 0xffff0000u); }
; __device__ __forceinline__ void lru_pass3_item(const float* __restrict__ LA, const float* __restrict__ LU, const float* __restrict__ AGG, const bf16_t* __restrict__ GP, bf16_t* __restrict__ O, int item, LAS unsigned char* lds) {
;     ...
;     if (half) { CX[(tid - 256) * 2] = cA; CX[(tid - 256) * 2 + 1] = cH; }
;     __syncthreads();
;     if (tid < 256) {
;         float h = CX[tid * 2] * cH + CX[tid * 2 + 1];
;         LAS unsigned* su = S + dir * 64 * 128 + ch;
; #pragma unroll 8
;         for (int t = 0; t < 64; ++t) { const int tt = dir ? 63 - t : t; const unsigned w = su[tt * 128]; h = (1.f - bflo(w)) * h + bfhi(w); su[tt * 128] = __float_as_uint(h); }
;     }
.LBB0_761:
	s_or_b64 exec, exec, s[16:17]
	s_and_saveexec_b64 s[0:1], vcc
	s_add_i32 s4, 0, 0x10000
	v_lshl_add_u32 v0, v25, 3, s4
	v_add_u32_e32 v0, 0xfffff800, v0
	v_mov_b32_e32 v3, v5
	ds_write_b64 v0, v[2:3]
	s_or_b64 exec, exec, s[0:1]
	v_cmp_gt_i32_e32 vcc, s93, v25
	s_waitcnt lgkmcnt(0)
	s_barrier
	s_and_saveexec_b64 s[0:1], vcc
	s_cbranch_execz .LBB0_688
	v_lshl_add_u32 v0, v25, 3, 0
	v_add_u32_e32 v0, 0x10000, v0
	ds_read_b64 v[0:1], v0
	v_lshlrev_b32_e32 v2, 15, v26
	v_lshlrev_b32_e32 v3, 2, v27
	s_mov_b32 s4, 0
	v_add3_u32 v2, 0, v2, v3
	s_waitcnt lgkmcnt(0)
	v_fmac_f32_e32 v1, v5, v0
	s_mov_b32 s5, 56
	v_mov_b32_e32 v5, 0x200
	v_mov_b32_e32 v6, 0xfffffe00
	v_mov_b32_e32 v9, 0x7e00
	v_cndmask_b32_e64 v5, v6, v5, s[2:3]
	v_cndmask_b32_e64 v6, v9, 0, s[2:3]
	v_add_u32_e32 v7, v2, v6
	v_mov_b32_e32 v8, v7
	ds_read_b32 v10, v7
	v_add_u32_e32 v7, v7, v5
	ds_read_b32 v11, v7
	v_add_u32_e32 v7, v7, v5
	ds_read_b32 v12, v7
	v_add_u32_e32 v7, v7, v5
	ds_read_b32 v13, v7
	v_add_u32_e32 v7, v7, v5
	ds_read_b32 v14, v7
	v_add_u32_e32 v7, v7, v5
	ds_read_b32 v15, v7
	v_add_u32_e32 v7, v7, v5
	ds_read_b32 v16, v7
	v_add_u32_e32 v7, v7, v5
	ds_read_b32 v17, v7
	v_add_u32_e32 v7, v7, v5
	s_waitcnt lgkmcnt(7)
	v_lshlrev_b32_e32 v4, 16, v10
	v_sub_f32_e32 v4, 1.0, v4
	v_and_b32_e32 v10, 0xffff0000, v10
	v_fma_f32 v1, v1, v4, v10
	ds_write_b32 v8, v1
	v_add_u32_e32 v8, v8, v5
	ds_read_b32 v10, v7
	v_add_u32_e32 v7, v7, v5
	s_waitcnt lgkmcnt(8)
	v_lshlrev_b32_e32 v4, 16, v11
	v_sub_f32_e32 v4, 1.0, v4
	v_and_b32_e32 v11, 0xffff0000, v11
	v_fma_f32 v1, v1, v4, v11
	ds_write_b32 v8, v1
	v_add_u32_e32 v8, v8, v5
	ds_read_b32 v11, v7
	v_add_u32_e32 v7, v7, v5
	s_waitcnt lgkmcnt(9)
	v_lshlrev_b32_e32 v4, 16, v12
	v_sub_f32_e32 v4, 1.0, v4
	v_and_b32_e32 v12, 0xffff0000, v12
	v_fma_f32 v1, v1, v4, v12
	ds_write_b32 v8, v1
	v_add_u32_e32 v8, v8, v5
	ds_read_b32 v12, v7
	v_add_u32_e32 v7, v7, v5
	s_waitcnt lgkmcnt(10)
	v_lshlrev_b32_e32 v4, 16, v13
	v_sub_f32_e32 v4, 1.0, v4
	v_and_b32_e32 v13, 0xffff0000, v13
	v_fma_f32 v1, v1, v4, v13
	ds_write_b32 v8, v1
	v_add_u32_e32 v8, v8, v5
	ds_read_b32 v13, v7
	v_add_u32_e32 v7, v7, v5
	s_waitcnt lgkmcnt(11)
	v_lshlrev_b32_e32 v4, 16, v14
	v_sub_f32_e32 v4, 1.0, v4
	v_and_b32_e32 v14, 0xffff0000, v14
	v_fma_f32 v1, v1, v4, v14
	ds_write_b32 v8, v1
	v_add_u32_e32 v8, v8, v5
	ds_read_b32 v14, v7
	v_add_u32_e32 v7, v7, v5
	s_waitcnt lgkmcnt(12)
	v_lshlrev_b32_e32 v4, 16, v15
	v_sub_f32_e32 v4, 1.0, v4
	v_and_b32_e32 v15, 0xffff0000, v15
	v_fma_f32 v1, v1, v4, v15
	ds_write_b32 v8, v1
	v_add_u32_e32 v8, v8, v5
	ds_read_b32 v15, v7
	v_add_u32_e32 v7, v7, v5
	s_waitcnt lgkmcnt(13)
	v_lshlrev_b32_e32 v4, 16, v16
	v_sub_f32_e32 v4, 1.0, v4
	v_and_b32_e32 v16, 0xffff0000, v16
	v_fma_f32 v1, v1, v4, v16
	ds_write_b32 v8, v1
	v_add_u32_e32 v8, v8, v5
	ds_read_b32 v16, v7
	v_add_u32_e32 v7, v7, v5
	s_waitcnt lgkmcnt(14)
	v_lshlrev_b32_e32 v4, 16, v17
	v_sub_f32_e32 v4, 1.0, v4
	v_and_b32_e32 v17, 0xffff0000, v17
	v_fma_f32 v1, v1, v4, v17
	ds_write_b32 v8, v1
	v_add_u32_e32 v8, v8, v5
	ds_read_b32 v17, v7
	v_add_u32_e32 v7, v7, v5
	s_waitcnt lgkmcnt(14)
	v_lshlrev_b32_e32 v4, 16, v10
	v_sub_f32_e32 v4, 1.0, v4
	v_and_b32_e32 v10, 0xffff0000, v10
	v_fma_f32 v1, v1, v4, v10
	ds_write_b32 v8, v1
	v_add_u32_e32 v8, v8, v5
	ds_read_b32 v10, v7
	v_add_u32_e32 v7, v7, v5
	s_waitcnt lgkmcnt(14)
	v_lshlrev_b32_e32 v4, 16, v11
	v_sub_f32_e32 v4, 1.0, v4
	v_and_b32_e32 v11, 0xffff0000, v11
	v_fma_f32 v1, v1, v4, v11
	ds_write_b32 v8, v1
	v_add_u32_e32 v8, v8, v5
	ds_read_b32 v11, v7
	v_add_u32_e32 v7, v7, v5
	s_waitcnt lgkmcnt(14)
	v_lshlrev_b32_e32 v4, 16, v12
	v_sub_f32_e32 v4, 1.0, v4
	v_and_b32_e32 v12, 0xffff0000, v12
	v_fma_f32 v1, v1, v4, v12
	ds_write_b32 v8, v1
	v_add_u32_e32 v8, v8, v5
	ds_read_b32 v12, v7
	v_add_u32_e32 v7, v7, v5
	s_waitcnt lgkmcnt(14)
	v_lshlrev_b32_e32 v4, 16, v13
	v_sub_f32_e32 v4, 1.0, v4
	v_and_b32_e32 v13, 0xffff0000, v13
	v_fma_f32 v1, v1, v4, v13
	ds_write_b32 v8, v1
	v_add_u32_e32 v8, v8, v5
	ds_read_b32 v13, v7
	v_add_u32_e32 v7, v7, v5
	s_waitcnt lgkmcnt(14)
	v_lshlrev_b32_e32 v4, 16, v14
	v_sub_f32_e32 v4, 1.0, v4
	v_and_b32_e32 v14, 0xffff0000, v14
	v_fma_f32 v1, v1, v4, v14
	ds_write_b32 v8, v1
	v_add_u32_e32 v8, v8, v5
	ds_read_b32 v14, v7
	v_add_u32_e32 v7, v7, v5
	s_waitcnt lgkmcnt(14)
	v_lshlrev_b32_e32 v4, 16, v15
	v_sub_f32_e32 v4, 1.0, v4
	v_and_b32_e32 v15, 0xffff0000, v15
	v_fma_f32 v1, v1, v4, v15
	ds_write_b32 v8, v1
	v_add_u32_e32 v8, v8, v5
	ds_read_b32 v15, v7
	v_add_u32_e32 v7, v7, v5
	s_waitcnt lgkmcnt(14)
	v_lshlrev_b32_e32 v4, 16, v16
	v_sub_f32_e32 v4, 1.0, v4
	v_and_b32_e32 v16, 0xffff0000, v16
	v_fma_f32 v1, v1, v4, v16
	ds_write_b32 v8, v1
	v_add_u32_e32 v8, v8, v5
	ds_read_b32 v16, v7
	v_add_u32_e32 v7, v7, v5
	s_waitcnt lgkmcnt(14)
	v_lshlrev_b32_e32 v4, 16, v17
	v_sub_f32_e32 v4, 1.0, v4
	v_and_b32_e32 v17, 0xffff0000, v17
	v_fma_f32 v1, v1, v4, v17
	ds_write_b32 v8, v1
	v_add_u32_e32 v8, v8, v5
	ds_read_b32 v17, v7
	v_add_u32_e32 v7, v7, v5
	s_waitcnt lgkmcnt(14)
	v_lshlrev_b32_e32 v4, 16, v10
	v_sub_f32_e32 v4, 1.0, v4
	v_and_b32_e32 v10, 0xffff0000, v10
	v_fma_f32 v1, v1, v4, v10
	ds_write_b32 v8, v1
	v_add_u32_e32 v8, v8, v5
	ds_read_b32 v10, v7
	v_add_u32_e32 v7, v7, v5
	s_waitcnt lgkmcnt(14)
	v_lshlrev_b32_e32 v4, 16, v11
	v_sub_f32_e32 v4, 1.0, v4
	v_and_b32_e32 v11, 0xffff0000, v11
	v_fma_f32 v1, v1, v4, v11
	ds_write_b32 v8, v1
	v_add_u32_e32 v8, v8, v5
	ds_read_b32 v11, v7
	v_add_u32_e32 v7, v7, v5
	s_waitcnt lgkmcnt(14)
	v_lshlrev_b32_e32 v4, 16, v12
	v_sub_f32_e32 v4, 1.0, v4
	v_and_b32_e32 v12, 0xffff0000, v12
	v_fma_f32 v1, v1, v4, v12
	ds_write_b32 v8, v1
	v_add_u32_e32 v8, v8, v5
	ds_read_b32 v12, v7
	v_add_u32_e32 v7, v7, v5
	s_waitcnt lgkmcnt(14)
; __device__ __forceinline__ float bflo(unsigned u) { return __uint_as_float(u << 16); }
; __device__ __forceinline__ float bfhi(unsigned u) { return __uint_as_float(u & 0xffff0000u); }
; __device__ __forceinline__ void lru_pass3_item(const float* __restrict__ LA, const float* __restrict__ LU, const float* __restrict__ AGG, const bf16_t* __restrict__ GP, bf16_t* __restrict__ O, int item, LAS unsigned char* lds) {
;     ...
; #pragma unroll 8
;         for (int t = 0; t < 64; ++t) { const int tt = dir ? 63 - t : t; const unsigned w = su[tt * 128]; h = (1.f - bflo(w)) * h + bfhi(w); su[tt * 128] = __float_as_uint(h); }
;     }
	v_lshlrev_b32_e32 v4, 16, v13
	v_sub_f32_e32 v4, 1.0, v4
	v_and_b32_e32 v13, 0xffff0000, v13
	v_fma_f32 v1, v1, v4, v13
	ds_write_b32 v8, v1
	v_add_u32_e32 v8, v8, v5
	ds_read_b32 v13, v7
	v_add_u32_e32 v7, v7, v5
	s_waitcnt lgkmcnt(14)
	v_lshlrev_b32_e32 v4, 16, v14
	v_sub_f32_e32 v4, 1.0, v4
	v_and_b32_e32 v14, 0xffff0000, v14
	v_fma_f32 v1, v1, v4, v14
	ds_write_b32 v8, v1
	v_add_u32_e32 v8, v8, v5
	ds_read_b32 v14, v7
	v_add_u32_e32 v7, v7, v5
	s_waitcnt lgkmcnt(14)
	v_lshlrev_b32_e32 v4, 16, v15
	v_sub_f32_e32 v4, 1.0, v4
	v_and_b32_e32 v15, 0xffff0000, v15
	v_fma_f32 v1, v1, v4, v15
	ds_write_b32 v8, v1
	v_add_u32_e32 v8, v8, v5
	ds_read_b32 v15, v7
	v_add_u32_e32 v7, v7, v5
	s_waitcnt lgkmcnt(14)
	v_lshlrev_b32_e32 v4, 16, v16
	v_sub_f32_e32 v4, 1.0, v4
	v_and_b32_e32 v16, 0xffff0000, v16
	v_fma_f32 v1, v1, v4, v16
	ds_write_b32 v8, v1
	v_add_u32_e32 v8, v8, v5
	ds_read_b32 v16, v7
	v_add_u32_e32 v7, v7, v5
	s_waitcnt lgkmcnt(14)
	v_lshlrev_b32_e32 v4, 16, v17
	v_sub_f32_e32 v4, 1.0, v4
	v_and_b32_e32 v17, 0xffff0000, v17
	v_fma_f32 v1, v1, v4, v17
	ds_write_b32 v8, v1
	v_add_u32_e32 v8, v8, v5
	ds_read_b32 v17, v7
	v_add_u32_e32 v7, v7, v5
	s_waitcnt lgkmcnt(14)
	v_lshlrev_b32_e32 v4, 16, v10
	v_sub_f32_e32 v4, 1.0, v4
	v_and_b32_e32 v10, 0xffff0000, v10
	v_fma_f32 v1, v1, v4, v10
	ds_write_b32 v8, v1
	v_add_u32_e32 v8, v8, v5
	ds_read_b32 v10, v7
	v_add_u32_e32 v7, v7, v5
	s_waitcnt lgkmcnt(14)
	v_lshlrev_b32_e32 v4, 16, v11
	v_sub_f32_e32 v4, 1.0, v4
	v_and_b32_e32 v11, 0xffff0000, v11
	v_fma_f32 v1, v1, v4, v11
	ds_write_b32 v8, v1
	v_add_u32_e32 v8, v8, v5
	ds_read_b32 v11, v7
	v_add_u32_e32 v7, v7, v5
	s_waitcnt lgkmcnt(14)
	v_lshlrev_b32_e32 v4, 16, v12
	v_sub_f32_e32 v4, 1.0, v4
	v_and_b32_e32 v12, 0xffff0000, v12
	v_fma_f32 v1, v1, v4, v12
	ds_write_b32 v8, v1
	v_add_u32_e32 v8, v8, v5
	ds_read_b32 v12, v7
	v_add_u32_e32 v7, v7, v5
	s_waitcnt lgkmcnt(14)
	v_lshlrev_b32_e32 v4, 16, v13
	v_sub_f32_e32 v4, 1.0, v4
	v_and_b32_e32 v13, 0xffff0000, v13
	v_fma_f32 v1, v1, v4, v13
	ds_write_b32 v8, v1
	v_add_u32_e32 v8, v8, v5
	ds_read_b32 v13, v7
	v_add_u32_e32 v7, v7, v5
	s_waitcnt lgkmcnt(14)
	v_lshlrev_b32_e32 v4, 16, v14
	v_sub_f32_e32 v4, 1.0, v4
	v_and_b32_e32 v14, 0xffff0000, v14
	v_fma_f32 v1, v1, v4, v14
	ds_write_b32 v8, v1
	v_add_u32_e32 v8, v8, v5
	ds_read_b32 v14, v7
	v_add_u32_e32 v7, v7, v5
	s_waitcnt lgkmcnt(14)
	v_lshlrev_b32_e32 v4, 16, v15
	v_sub_f32_e32 v4, 1.0, v4
	v_and_b32_e32 v15, 0xffff0000, v15
	v_fma_f32 v1, v1, v4, v15
	ds_write_b32 v8, v1
	v_add_u32_e32 v8, v8, v5
	ds_read_b32 v15, v7
	v_add_u32_e32 v7, v7, v5
	s_waitcnt lgkmcnt(14)
	v_lshlrev_b32_e32 v4, 16, v16
	v_sub_f32_e32 v4, 1.0, v4
	v_and_b32_e32 v16, 0xffff0000, v16
	v_fma_f32 v1, v1, v4, v16
	ds_write_b32 v8, v1
	v_add_u32_e32 v8, v8, v5
	ds_read_b32 v16, v7
	v_add_u32_e32 v7, v7, v5
	s_waitcnt lgkmcnt(14)
	v_lshlrev_b32_e32 v4, 16, v17
	v_sub_f32_e32 v4, 1.0, v4
	v_and_b32_e32 v17, 0xffff0000, v17
	v_fma_f32 v1, v1, v4, v17
	ds_write_b32 v8, v1
	v_add_u32_e32 v8, v8, v5
	ds_read_b32 v17, v7
	v_add_u32_e32 v7, v7, v5
	s_waitcnt lgkmcnt(14)
	v_lshlrev_b32_e32 v4, 16, v10
	v_sub_f32_e32 v4, 1.0, v4
	v_and_b32_e32 v10, 0xffff0000, v10
	v_fma_f32 v1, v1, v4, v10
	ds_write_b32 v8, v1
	v_add_u32_e32 v8, v8, v5
	ds_read_b32 v10, v7
	v_add_u32_e32 v7, v7, v5
	s_waitcnt lgkmcnt(14)
	v_lshlrev_b32_e32 v4, 16, v11
	v_sub_f32_e32 v4, 1.0, v4
	v_and_b32_e32 v11, 0xffff0000, v11
	v_fma_f32 v1, v1, v4, v11
	ds_write_b32 v8, v1
	v_add_u32_e32 v8, v8, v5
	ds_read_b32 v11, v7
	v_add_u32_e32 v7, v7, v5
	s_waitcnt lgkmcnt(14)
	v_lshlrev_b32_e32 v4, 16, v12
	v_sub_f32_e32 v4, 1.0, v4
	v_and_b32_e32 v12, 0xffff0000, v12
	v_fma_f32 v1, v1, v4, v12
	ds_write_b32 v8, v1
	v_add_u32_e32 v8, v8, v5
	ds_read_b32 v12, v7
	v_add_u32_e32 v7, v7, v5
	s_waitcnt lgkmcnt(14)
	v_lshlrev_b32_e32 v4, 16, v13
	v_sub_f32_e32 v4, 1.0, v4
	v_and_b32_e32 v13, 0xffff0000, v13
	v_fma_f32 v1, v1, v4, v13
	ds_write_b32 v8, v1
	v_add_u32_e32 v8, v8, v5
	ds_read_b32 v13, v7
	v_add_u32_e32 v7, v7, v5
	s_waitcnt lgkmcnt(14)
	v_lshlrev_b32_e32 v4, 16, v14
	v_sub_f32_e32 v4, 1.0, v4
	v_and_b32_e32 v14, 0xffff0000, v14
	v_fma_f32 v1, v1, v4, v14
	ds_write_b32 v8, v1
	v_add_u32_e32 v8, v8, v5
	ds_read_b32 v14, v7
	v_add_u32_e32 v7, v7, v5
	s_waitcnt lgkmcnt(14)
	v_lshlrev_b32_e32 v4, 16, v15
	v_sub_f32_e32 v4, 1.0, v4
	v_and_b32_e32 v15, 0xffff0000, v15
	v_fma_f32 v1, v1, v4, v15
	ds_write_b32 v8, v1
	v_add_u32_e32 v8, v8, v5
	ds_read_b32 v15, v7
	v_add_u32_e32 v7, v7, v5
	s_waitcnt lgkmcnt(14)
	v_lshlrev_b32_e32 v4, 16, v16
	v_sub_f32_e32 v4, 1.0, v4
	v_and_b32_e32 v16, 0xffff0000, v16
	v_fma_f32 v1, v1, v4, v16
	ds_write_b32 v8, v1
	v_add_u32_e32 v8, v8, v5
	ds_read_b32 v16, v7
	v_add_u32_e32 v7, v7, v5
	s_waitcnt lgkmcnt(14)
	v_lshlrev_b32_e32 v4, 16, v17
	v_sub_f32_e32 v4, 1.0, v4
	v_and_b32_e32 v17, 0xffff0000, v17
	v_fma_f32 v1, v1, v4, v17
	ds_write_b32 v8, v1
	v_add_u32_e32 v8, v8, v5
	ds_read_b32 v17, v7
	v_add_u32_e32 v7, v7, v5
	s_waitcnt lgkmcnt(14)
	v_lshlrev_b32_e32 v4, 16, v10
	v_sub_f32_e32 v4, 1.0, v4
	v_and_b32_e32 v10, 0xffff0000, v10
	v_fma_f32 v1, v1, v4, v10
	ds_write_b32 v8, v1
	v_add_u32_e32 v8, v8, v5
	ds_read_b32 v10, v7
	v_add_u32_e32 v7, v7, v5
	s_waitcnt lgkmcnt(14)
; __device__ __forceinline__ float bflo(unsigned u) { return __uint_as_float(u << 16); }
; __device__ __forceinline__ float bfhi(unsigned u) { return __uint_as_float(u & 0xffff0000u); }
; __device__ __forceinline__ void lru_pass3_item(const float* __restrict__ LA, const float* __restrict__ LU, const float* __restrict__ AGG, const bf16_t* __restrict__ GP, bf16_t* __restrict__ O, int item, LAS unsigned char* lds) {
;     ...
; #pragma unroll 8
;         for (int t = 0; t < 64; ++t) { const int tt = dir ? 63 - t : t; const unsigned w = su[tt * 128]; h = (1.f - bflo(w)) * h + bfhi(w); su[tt * 128] = __float_as_uint(h); }
;     }
	v_lshlrev_b32_e32 v4, 16, v11
	v_sub_f32_e32 v4, 1.0, v4
	v_and_b32_e32 v11, 0xffff0000, v11
	v_fma_f32 v1, v1, v4, v11
	ds_write_b32 v8, v1
	v_add_u32_e32 v8, v8, v5
	ds_read_b32 v11, v7
	v_add_u32_e32 v7, v7, v5
	s_waitcnt lgkmcnt(14)
	v_lshlrev_b32_e32 v4, 16, v12
	v_sub_f32_e32 v4, 1.0, v4
	v_and_b32_e32 v12, 0xffff0000, v12
	v_fma_f32 v1, v1, v4, v12
	ds_write_b32 v8, v1
	v_add_u32_e32 v8, v8, v5
	ds_read_b32 v12, v7
	v_add_u32_e32 v7, v7, v5
	s_waitcnt lgkmcnt(14)
	v_lshlrev_b32_e32 v4, 16, v13
	v_sub_f32_e32 v4, 1.0, v4
	v_and_b32_e32 v13, 0xffff0000, v13
	v_fma_f32 v1, v1, v4, v13
	ds_write_b32 v8, v1
	v_add_u32_e32 v8, v8, v5
	ds_read_b32 v13, v7
	v_add_u32_e32 v7, v7, v5
	s_waitcnt lgkmcnt(14)
	v_lshlrev_b32_e32 v4, 16, v14
	v_sub_f32_e32 v4, 1.0, v4
	v_and_b32_e32 v14, 0xffff0000, v14
	v_fma_f32 v1, v1, v4, v14
	ds_write_b32 v8, v1
	v_add_u32_e32 v8, v8, v5
	ds_read_b32 v14, v7
	v_add_u32_e32 v7, v7, v5
	s_waitcnt lgkmcnt(14)
	v_lshlrev_b32_e32 v4, 16, v15
	v_sub_f32_e32 v4, 1.0, v4
	v_and_b32_e32 v15, 0xffff0000, v15
	v_fma_f32 v1, v1, v4, v15
	ds_write_b32 v8, v1
	v_add_u32_e32 v8, v8, v5
	ds_read_b32 v15, v7
	v_add_u32_e32 v7, v7, v5
	s_waitcnt lgkmcnt(14)
	v_lshlrev_b32_e32 v4, 16, v16
	v_sub_f32_e32 v4, 1.0, v4
	v_and_b32_e32 v16, 0xffff0000, v16
	v_fma_f32 v1, v1, v4, v16
	ds_write_b32 v8, v1
	v_add_u32_e32 v8, v8, v5
	ds_read_b32 v16, v7
	v_add_u32_e32 v7, v7, v5
	s_waitcnt lgkmcnt(14)
	v_lshlrev_b32_e32 v4, 16, v17
	v_sub_f32_e32 v4, 1.0, v4
	v_and_b32_e32 v17, 0xffff0000, v17
	v_fma_f32 v1, v1, v4, v17
	ds_write_b32 v8, v1
	v_add_u32_e32 v8, v8, v5
	ds_read_b32 v17, v7
	v_add_u32_e32 v7, v7, v5
	s_waitcnt lgkmcnt(14)
	v_lshlrev_b32_e32 v4, 16, v10
	v_sub_f32_e32 v4, 1.0, v4
	v_and_b32_e32 v10, 0xffff0000, v10
	v_fma_f32 v1, v1, v4, v10
	ds_write_b32 v8, v1
	v_add_u32_e32 v8, v8, v5
	ds_read_b32 v10, v7
	v_add_u32_e32 v7, v7, v5
	s_waitcnt lgkmcnt(14)
	v_lshlrev_b32_e32 v4, 16, v11
	v_sub_f32_e32 v4, 1.0, v4
	v_and_b32_e32 v11, 0xffff0000, v11
	v_fma_f32 v1, v1, v4, v11
	ds_write_b32 v8, v1
	v_add_u32_e32 v8, v8, v5
	ds_read_b32 v11, v7
	v_add_u32_e32 v7, v7, v5
	s_waitcnt lgkmcnt(14)
	v_lshlrev_b32_e32 v4, 16, v12
	v_sub_f32_e32 v4, 1.0, v4
	v_and_b32_e32 v12, 0xffff0000, v12
	v_fma_f32 v1, v1, v4, v12
	ds_write_b32 v8, v1
	v_add_u32_e32 v8, v8, v5
	ds_read_b32 v12, v7
	v_add_u32_e32 v7, v7, v5
	s_waitcnt lgkmcnt(14)
	v_lshlrev_b32_e32 v4, 16, v13
	v_sub_f32_e32 v4, 1.0, v4
	v_and_b32_e32 v13, 0xffff0000, v13
	v_fma_f32 v1, v1, v4, v13
	ds_write_b32 v8, v1
	v_add_u32_e32 v8, v8, v5
	ds_read_b32 v13, v7
	v_add_u32_e32 v7, v7, v5
	s_waitcnt lgkmcnt(14)
	v_lshlrev_b32_e32 v4, 16, v14
	v_sub_f32_e32 v4, 1.0, v4
	v_and_b32_e32 v14, 0xffff0000, v14
	v_fma_f32 v1, v1, v4, v14
	ds_write_b32 v8, v1
	v_add_u32_e32 v8, v8, v5
	ds_read_b32 v14, v7
	v_add_u32_e32 v7, v7, v5
	s_waitcnt lgkmcnt(14)
	v_lshlrev_b32_e32 v4, 16, v15
	v_sub_f32_e32 v4, 1.0, v4
	v_and_b32_e32 v15, 0xffff0000, v15
	v_fma_f32 v1, v1, v4, v15
	ds_write_b32 v8, v1
	v_add_u32_e32 v8, v8, v5
	ds_read_b32 v15, v7
	v_add_u32_e32 v7, v7, v5
	s_waitcnt lgkmcnt(14)
	v_lshlrev_b32_e32 v4, 16, v16
	v_sub_f32_e32 v4, 1.0, v4
	v_and_b32_e32 v16, 0xffff0000, v16
	v_fma_f32 v1, v1, v4, v16
	ds_write_b32 v8, v1
	v_add_u32_e32 v8, v8, v5
	ds_read_b32 v16, v7
	v_add_u32_e32 v7, v7, v5
	s_waitcnt lgkmcnt(14)
	v_lshlrev_b32_e32 v4, 16, v17
	v_sub_f32_e32 v4, 1.0, v4
	v_and_b32_e32 v17, 0xffff0000, v17
	v_fma_f32 v1, v1, v4, v17
	ds_write_b32 v8, v1
	v_add_u32_e32 v8, v8, v5
	ds_read_b32 v17, v7
	s_waitcnt lgkmcnt(14)
	v_lshlrev_b32_e32 v4, 16, v10
	v_sub_f32_e32 v4, 1.0, v4
	v_and_b32_e32 v10, 0xffff0000, v10
	v_fma_f32 v1, v1, v4, v10
	ds_write_b32 v8, v1
	v_add_u32_e32 v8, v8, v5
	s_waitcnt lgkmcnt(13)
	v_lshlrev_b32_e32 v4, 16, v11
	v_sub_f32_e32 v4, 1.0, v4
	v_and_b32_e32 v11, 0xffff0000, v11
	v_fma_f32 v1, v1, v4, v11
	ds_write_b32 v8, v1
	v_add_u32_e32 v8, v8, v5
	s_waitcnt lgkmcnt(12)
	v_lshlrev_b32_e32 v4, 16, v12
	v_sub_f32_e32 v4, 1.0, v4
	v_and_b32_e32 v12, 0xffff0000, v12
	v_fma_f32 v1, v1, v4, v12
	ds_write_b32 v8, v1
	v_add_u32_e32 v8, v8, v5
	s_waitcnt lgkmcnt(11)
	v_lshlrev_b32_e32 v4, 16, v13
	v_sub_f32_e32 v4, 1.0, v4
	v_and_b32_e32 v13, 0xffff0000, v13
	v_fma_f32 v1, v1, v4, v13
	ds_write_b32 v8, v1
	v_add_u32_e32 v8, v8, v5
	s_waitcnt lgkmcnt(10)
	v_lshlrev_b32_e32 v4, 16, v14
	v_sub_f32_e32 v4, 1.0, v4
	v_and_b32_e32 v14, 0xffff0000, v14
	v_fma_f32 v1, v1, v4, v14
	ds_write_b32 v8, v1
	v_add_u32_e32 v8, v8, v5
	s_waitcnt lgkmcnt(9)
	v_lshlrev_b32_e32 v4, 16, v15
	v_sub_f32_e32 v4, 1.0, v4
	v_and_b32_e32 v15, 0xffff0000, v15
	v_fma_f32 v1, v1, v4, v15
	ds_write_b32 v8, v1
	v_add_u32_e32 v8, v8, v5
	s_waitcnt lgkmcnt(8)
	v_lshlrev_b32_e32 v4, 16, v16
	v_sub_f32_e32 v4, 1.0, v4
	v_and_b32_e32 v16, 0xffff0000, v16
	v_fma_f32 v1, v1, v4, v16
	ds_write_b32 v8, v1
	v_add_u32_e32 v8, v8, v5
	s_waitcnt lgkmcnt(7)
	v_lshlrev_b32_e32 v4, 16, v17
	v_sub_f32_e32 v4, 1.0, v4
	v_and_b32_e32 v17, 0xffff0000, v17
	v_fma_f32 v1, v1, v4, v17
	ds_write_b32 v8, v1
	s_branch .LBB0_688
